# attention loops: cross-half row-sum exchange deferred to loop exit (per-half partial sums, fused into one fma per tile)
# speedup vs baseline: 1.0012x; 1.0012x over previous
; #define SBAR() __builtin_amdgcn_sched_barrier(0)
; __device__ __forceinline__ void finishSM(f32x16& p0, f32x16& p1, float alpha, float& l_reg, bf16x8& pa0, bf16x8& pa1, bf16x8& pa2, bf16x8& pa3) {
; #pragma unroll
;   for (int r = 0; r < 16; ++r) p1[r] = __builtin_amdgcn_exp2f(p1[r]);
;   float ps = 0;
; #pragma unroll
;   for (int r = 0; r < 16; ++r) ps += p0[r];
; #pragma unroll
;   for (int r = 0; r < 16; ++r) ps += p1[r];
;   { auto rr = __builtin_amdgcn_permlane32_swap(__float_as_uint(ps), __float_as_uint(ps), false, false);
;     ps = __uint_as_float(rr[0]) + __uint_as_float(rr[1]); }
;   l_reg = l_reg * alpha + ps;
;     ...
;   PK4(p0, 0, pa0); PK4(p0, 8, pa1); PK4(p1, 0, pa2); PK4(p1, 8, pa3);
;     ...
; }
; template <int DK, bool QL>
; __device__ __forceinline__ void qkt(f32x16& p0, f32x16& p1, const bf16* Ks, const bf16x8* qr, const char* ql, int r32, int hi) {
;   p0 = f32x16{}; p1 = f32x16{};
; #pragma unroll
;   for (int d0 = 0; d0 < DK / 16; ++d0) { int cb = (d0 * 16 + hi * 8) * 2;
;     const bf16x8 qv = QL ? *reinterpret_cast<const bf16x8*>(ql + d0 * 1024) : qr[d0];
;     bf16x8 b0 = *reinterpret_cast<const bf16x8*>((const char*)Ks + kswz<DK>(r32, cb));
;     bf16x8 b1 = *reinterpret_cast<const bf16x8*>((const char*)Ks + kswz<DK>(32 + r32, cb));
;     p0 = __builtin_amdgcn_mfma_f32_32x32x16_bf16(b0, qv, p0, 0, 0, 0);
;     p1 = __builtin_amdgcn_mfma_f32_32x32x16_bf16(b1, qv, p1, 0, 0, 0); }
; }
; template <int OFF> __device__ __forceinline__ s16x4 tr_read(int vb) {
;   s16x4 r; asm volatile("ds_read_b64_tr_b16 %0, %1 offset:%2" : "=&v"(r) : "v"(vb), "i"(OFF) : "memory"); return r;
; }
; template <int D0> __device__ __forceinline__ void pv_one(f32x16& od, int vb, bf16x8 pa0, bf16x8 pa1, bf16x8 pa2, bf16x8 pa3) {
;   const s16x4 l0 = tr_read<v_rd_off(D0, 0, 0)>(vb), h0 = tr_read<v_rd_off(D0, 0, 1)>(vb), l1 = tr_read<v_rd_off(D0, 1, 0)>(vb), h1 = tr_read<v_rd_off(D0, 1, 1)>(vb);
;   const s16x4 l2 = tr_read<v_rd_off(D0, 2, 0)>(vb), h2 = tr_read<v_rd_off(D0, 2, 1)>(vb), l3 = tr_read<v_rd_off(D0, 3, 0)>(vb), h3 = tr_read<v_rd_off(D0, 3, 1)>(vb);
;   asm volatile("s_waitcnt lgkmcnt(0)" ::: "memory"); SBAR();
;     ...
;   od = __builtin_amdgcn_mfma_f32_32x32x16_bf16(pa0, PK(l0, h0), od, 0, 0, 0);
;   od = __builtin_amdgcn_mfma_f32_32x32x16_bf16(pa1, PK(l1, h1), od, 0, 0, 0);
;   od = __builtin_amdgcn_mfma_f32_32x32x16_bf16(pa2, PK(l2, h2), od, 0, 0, 0);
.LBB0_660:
	ds_read_b128 v[66:69], v153
	ds_read_b128 v[70:73], v159 offset:49152
	ds_read_b128 v[74:77], v159 offset:57344
	ds_read_b128 v[218:221], v153 offset:1024
	ds_read_b128 v[222:225], v207 offset:49152
	ds_read_b128 v[226:229], v207 offset:57344
	v_add_f32_e32 v130, v216, v145
	s_waitcnt lgkmcnt(4)
	v_mfma_f32_32x32x16_bf16 v[82:97], v[70:73], v[66:69], 0
	v_add_f32_e32 v130, v131, v130
	v_add_f32_e32 v130, v215, v130
	v_add_f32_e32 v130, v132, v130
	v_add_f32_e32 v130, v144, v130
	v_add_f32_e32 v130, v133, v130
	v_add_f32_e32 v130, v143, v130
	v_add_f32_e32 v130, v140, v130
	s_waitcnt lgkmcnt(3)
	v_mfma_f32_32x32x16_bf16 v[66:81], v[74:77], v[66:69], 0
	v_add_f32_e32 v130, v142, v130
	v_add_f32_e32 v130, v139, v130
	v_add_f32_e32 v130, v141, v130
	v_exp_f32_e32 v126, v126
	v_add_f32_e32 v130, v136, v130
	v_exp_f32_e32 v127, v127
	v_add_f32_e32 v130, v138, v130
	s_waitcnt lgkmcnt(1)
	v_mfma_f32_32x32x16_bf16 v[82:97], v[222:225], v[218:221], v[82:97]
	v_exp_f32_e32 v124, v124
	v_add_f32_e32 v130, v135, v130
	v_exp_f32_e32 v125, v125
	v_add_f32_e32 v130, v137, v130
	v_exp_f32_e32 v118, v118
	v_add_f32_e32 v130, v126, v130
	v_exp_f32_e32 v119, v119
	s_waitcnt lgkmcnt(0)
	v_mfma_f32_32x32x16_bf16 v[66:81], v[226:229], v[218:221], v[66:81]
	ds_read_b128 v[218:221], v153 offset:2048
	ds_read_b128 v[222:225], v161 offset:49152
	ds_read_b128 v[226:229], v161 offset:57344
	v_add_f32_e32 v130, v127, v130
	v_exp_f32_e32 v116, v116
	v_add_f32_e32 v130, v124, v130
	v_exp_f32_e32 v117, v117
	v_add_f32_e32 v130, v125, v130
	v_exp_f32_e32 v114, v114
	s_waitcnt lgkmcnt(1)
	v_mfma_f32_32x32x16_bf16 v[82:97], v[222:225], v[218:221], v[82:97]
	v_add_f32_e32 v130, v118, v130
	v_exp_f32_e32 v115, v115
	v_add_f32_e32 v130, v119, v130
	v_exp_f32_e32 v128, v128
	v_add_f32_e32 v130, v116, v130
	v_exp_f32_e32 v129, v129
	v_add_f32_e32 v130, v117, v130
	s_waitcnt lgkmcnt(0)
	v_mfma_f32_32x32x16_bf16 v[66:81], v[226:229], v[218:221], v[66:81]
	ds_read_b128 v[218:221], v153 offset:3072
	ds_read_b128 v[222:225], v160 offset:49152
	ds_read_b128 v[226:229], v160 offset:57344
	v_exp_f32_e32 v122, v122
	v_add_f32_e32 v130, v114, v130
	v_exp_f32_e32 v123, v123
	v_add_f32_e32 v130, v115, v130
	v_exp_f32_e32 v120, v120
	v_add_f32_e32 v130, v128, v130
	s_waitcnt lgkmcnt(1)
	v_mfma_f32_32x32x16_bf16 v[82:97], v[222:225], v[218:221], v[82:97]
	v_exp_f32_e32 v121, v121
	v_add_f32_e32 v130, v129, v130
	v_add_f32_e32 v130, v122, v130
	v_add_f32_e32 v130, v123, v130
	v_add_f32_e32 v130, v120, v130
	v_add_f32_e32 v212, v121, v130
	s_waitcnt lgkmcnt(0)
	v_mfma_f32_32x32x16_bf16 v[66:81], v[226:229], v[218:221], v[66:81]
	ds_read_b128 v[218:221], v153 offset:4096
	ds_read_b128 v[222:225], v158 offset:49152
	ds_read_b128 v[226:229], v158 offset:57344
	s_waitcnt lgkmcnt(1)
	v_mfma_f32_32x32x16_bf16 v[82:97], v[222:225], v[218:221], v[82:97]
	s_waitcnt lgkmcnt(0)
	v_mfma_f32_32x32x16_bf16 v[66:81], v[226:229], v[218:221], v[66:81]
	ds_read_b128 v[218:221], v153 offset:5120
	ds_read_b128 v[222:225], v156 offset:49152
	ds_read_b128 v[226:229], v156 offset:57344
	s_waitcnt lgkmcnt(1)
	v_mfma_f32_32x32x16_bf16 v[82:97], v[222:225], v[218:221], v[82:97]
	s_waitcnt lgkmcnt(0)
	v_mfma_f32_32x32x16_bf16 v[66:81], v[226:229], v[218:221], v[66:81]
	ds_read_b128 v[218:221], v153 offset:6144
	ds_read_b128 v[222:225], v157 offset:49152
	ds_read_b128 v[226:229], v157 offset:57344
	s_waitcnt lgkmcnt(1)
	v_mfma_f32_32x32x16_bf16 v[82:97], v[222:225], v[218:221], v[82:97]
	s_waitcnt lgkmcnt(0)
	v_mfma_f32_32x32x16_bf16 v[66:81], v[226:229], v[218:221], v[66:81]
	ds_read_b128 v[218:221], v153 offset:7168
	ds_read_b128 v[222:225], v176 offset:49152
	ds_read_b128 v[226:229], v176 offset:57344
	v_cvt_pk_bf16_f32 v130, v145, v216
	v_cvt_pk_bf16_f32 v131, v131, v215
	v_cvt_pk_bf16_f32 v132, v132, v144
	v_cvt_pk_bf16_f32 v133, v133, v143
	v_cvt_pk_bf16_f32 v140, v140, v142
	v_cvt_pk_bf16_f32 v141, v139, v141
	s_waitcnt lgkmcnt(1)
	v_mfma_f32_32x32x16_bf16 v[82:97], v[222:225], v[218:221], v[82:97]
	v_cvt_pk_bf16_f32 v142, v136, v138
	v_cvt_pk_bf16_f32 v143, v135, v137
	v_cvt_pk_bf16_f32 v136, v126, v127
	v_cvt_pk_bf16_f32 v137, v124, v125
	v_cvt_pk_bf16_f32 v138, v118, v119
	v_cvt_pk_bf16_f32 v139, v116, v117
	v_cvt_pk_bf16_f32 v214, v114, v115
	s_waitcnt lgkmcnt(0)
	v_mfma_f32_32x32x16_bf16 v[66:81], v[226:229], v[218:221], v[66:81]
	v_cvt_pk_bf16_f32 v215, v128, v129
	v_cvt_pk_bf16_f32 v216, v122, v123
	v_cvt_pk_bf16_f32 v217, v120, v121
	s_mov_b32 s2, 0xfff10000
	v_add_co_u32_e32 v118, vcc, s2, v146
	s_mov_b32 s2, 0xfff60000
	s_nop 0
	v_addc_co_u32_e32 v119, vcc, -1, v147, vcc
	v_add_co_u32_e32 v122, vcc, s2, v146
	s_nop 1
	v_addc_co_u32_e32 v123, vcc, -1, v147, vcc
	v_lshl_add_u64 v[164:165], v[118:119], 0, v[178:179]
	global_load_dwordx4 v[244:247], v[164:165], off
	s_nop 0
	global_load_dwordx4 v[118:121], v[118:119], off offset:-512
	s_nop 0
	v_lshl_add_u64 v[166:167], v[122:123], 0, v[178:179]
	global_load_dwordx4 v[194:197], v[166:167], off
	s_nop 0
	global_load_dwordx4 v[122:125], v[122:123], off offset:-512
	ds_read_b64_tr_b16 v[218:219], v152 offset:0
	ds_read_b64_tr_b16 v[220:221], v152 offset:0x800
	ds_read_b64_tr_b16 v[222:223], v152 offset:0x1000
	ds_read_b64_tr_b16 v[224:225], v152 offset:0x1800
	ds_read_b64_tr_b16 v[226:227], v152 offset:0x2000
	ds_read_b64_tr_b16 v[228:229], v152 offset:0x2800
	ds_read_b64_tr_b16 v[230:231], v152 offset:0x3000
	ds_read_b64_tr_b16 v[232:233], v152 offset:0x3800
	s_waitcnt lgkmcnt(4)
; #define SBAR() __builtin_amdgcn_sched_barrier(0)
; __device__ __forceinline__ void partialSM(f32x16& p0, f32x16& p1, float& m_reg, float& mn, float& alpha, float C, float thrRaw) {
;   float pmax = p0[0];
; #pragma unroll
;   for (int r = 1; r < 16; ++r) pmax = fmaxf(pmax, p0[r]);
; #pragma unroll
;   for (int r = 0; r < 16; ++r) pmax = fmaxf(pmax, p1[r]);
;   { auto rr = __builtin_amdgcn_permlane32_swap(__float_as_uint(pmax), __float_as_uint(pmax), false, false);
;     pmax = fmaxf(__uint_as_float(rr[0]), __uint_as_float(rr[1])); }
;   if (__builtin_expect(__all(pmax - m_reg <= thrRaw), 1)) { mn = m_reg; alpha = 1.f; }
;   else { mn = fmaxf(m_reg, pmax); alpha = __builtin_amdgcn_exp2f((m_reg - mn) * C); m_reg = mn; }
; template <int D0> __device__ __forceinline__ void pv_one(f32x16& od, int vb, bf16x8 pa0, bf16x8 pa1, bf16x8 pa2, bf16x8 pa3) {
;   const s16x4 l0 = tr_read<v_rd_off(D0, 0, 0)>(vb), h0 = tr_read<v_rd_off(D0, 0, 1)>(vb), l1 = tr_read<v_rd_off(D0, 1, 0)>(vb), h1 = tr_read<v_rd_off(D0, 1, 1)>(vb);
;   const s16x4 l2 = tr_read<v_rd_off(D0, 2, 0)>(vb), h2 = tr_read<v_rd_off(D0, 2, 1)>(vb), l3 = tr_read<v_rd_off(D0, 3, 0)>(vb), h3 = tr_read<v_rd_off(D0, 3, 1)>(vb);
;   asm volatile("s_waitcnt lgkmcnt(0)" ::: "memory"); SBAR();
;     ...
;   od = __builtin_amdgcn_mfma_f32_32x32x16_bf16(pa0, PK(l0, h0), od, 0, 0, 0);
;   od = __builtin_amdgcn_mfma_f32_32x32x16_bf16(pa1, PK(l1, h1), od, 0, 0, 0);
;   od = __builtin_amdgcn_mfma_f32_32x32x16_bf16(pa2, PK(l2, h2), od, 0, 0, 0);
;   od = __builtin_amdgcn_mfma_f32_32x32x16_bf16(pa3, PK(l3, h3), od, 0, 0, 0);
;     ...
; }
; __device__ __forceinline__ void pv_d0(f32x16* o, int vb, bf16x8 pa0, bf16x8 pa1, bf16x8 pa2, bf16x8 pa3) {
;   pv_one<0>(o[0], vb, pa0, pa1, pa2, pa3); pv_one<1>(o[1], vb, pa0, pa1, pa2, pa3); pv_one<2>(o[2], vb, pa0, pa1, pa2, pa3); pv_one<3>(o[3], vb, pa0, pa1, pa2, pa3);
	s_nop 0
	v_mfma_f32_32x32x16_bf16 v[18:33], v[130:133], v[218:221], v[18:33]
	ds_read_b64_tr_b16 v[218:219], v152 offset:0x200
	ds_read_b64_tr_b16 v[220:221], v152 offset:0xa00
	v_mfma_f32_32x32x16_bf16 v[18:33], v[140:143], v[222:225], v[18:33]
	ds_read_b64_tr_b16 v[222:223], v152 offset:0x1200
	ds_read_b64_tr_b16 v[224:225], v152 offset:0x1a00
	s_waitcnt lgkmcnt(4)
	v_mfma_f32_32x32x16_bf16 v[18:33], v[136:139], v[226:229], v[18:33]
	ds_read_b64_tr_b16 v[226:227], v152 offset:0x2200
	ds_read_b64_tr_b16 v[228:229], v152 offset:0x2a00
	v_mfma_f32_32x32x16_bf16 v[18:33], v[214:217], v[230:233], v[18:33]
	ds_read_b64_tr_b16 v[230:231], v152 offset:0x3200
	ds_read_b64_tr_b16 v[232:233], v152 offset:0x3a00
	s_waitcnt lgkmcnt(4)
	v_mfma_f32_32x32x16_bf16 v[50:65], v[130:133], v[218:221], v[50:65]
	ds_read_b64_tr_b16 v[218:219], v152 offset:0x400
	ds_read_b64_tr_b16 v[220:221], v152 offset:0xc00
	v_mfma_f32_32x32x16_bf16 v[50:65], v[140:143], v[222:225], v[50:65]
	ds_read_b64_tr_b16 v[222:223], v152 offset:0x1400
	ds_read_b64_tr_b16 v[224:225], v152 offset:0x1c00
	s_waitcnt lgkmcnt(4)
	v_mfma_f32_32x32x16_bf16 v[50:65], v[136:139], v[226:229], v[50:65]
	ds_read_b64_tr_b16 v[226:227], v152 offset:0x2400
	ds_read_b64_tr_b16 v[228:229], v152 offset:0x2c00
	v_mfma_f32_32x32x16_bf16 v[50:65], v[214:217], v[230:233], v[50:65]
	ds_read_b64_tr_b16 v[230:231], v152 offset:0x3400
	ds_read_b64_tr_b16 v[232:233], v152 offset:0x3c00
	s_waitcnt lgkmcnt(4)
	v_mfma_f32_32x32x16_bf16 v[2:17], v[130:133], v[218:221], v[2:17]
	ds_read_b64_tr_b16 v[218:219], v152 offset:0x600
	ds_read_b64_tr_b16 v[220:221], v152 offset:0xe00
	v_mfma_f32_32x32x16_bf16 v[2:17], v[140:143], v[222:225], v[2:17]
	ds_read_b64_tr_b16 v[222:223], v152 offset:0x1600
	ds_read_b64_tr_b16 v[224:225], v152 offset:0x1e00
	s_waitcnt lgkmcnt(4)
	v_mfma_f32_32x32x16_bf16 v[2:17], v[136:139], v[226:229], v[2:17]
	ds_read_b64_tr_b16 v[226:227], v152 offset:0x2600
	ds_read_b64_tr_b16 v[228:229], v152 offset:0x2e00
	v_mfma_f32_32x32x16_bf16 v[2:17], v[214:217], v[230:233], v[2:17]
	ds_read_b64_tr_b16 v[230:231], v152 offset:0x3600
	ds_read_b64_tr_b16 v[232:233], v152 offset:0x3e00
	s_waitcnt lgkmcnt(6)
	v_mfma_f32_32x32x16_bf16 v[34:49], v[130:133], v[218:221], v[34:49]
	v_max_f32_e32 v130, v83, v82
	v_max3_f32 v130, v130, v84, v85
	v_max3_f32 v130, v130, v86, v87
	v_max3_f32 v130, v130, v88, v89
	v_max3_f32 v130, v130, v90, v91
	v_max3_f32 v130, v130, v92, v93
	v_max3_f32 v130, v130, v94, v95
	s_waitcnt lgkmcnt(4)
	v_mfma_f32_32x32x16_bf16 v[34:49], v[140:143], v[222:225], v[34:49]
	v_max3_f32 v130, v130, v96, v97
	v_max3_f32 v130, v130, v66, v67
	v_max3_f32 v130, v130, v68, v69
	v_max3_f32 v130, v130, v70, v71
	v_max3_f32 v130, v130, v72, v73
	v_max3_f32 v130, v130, v74, v75
	v_max3_f32 v130, v130, v76, v77
	v_max3_f32 v130, v130, v78, v79
	s_waitcnt lgkmcnt(2)
	v_mfma_f32_32x32x16_bf16 v[34:49], v[136:139], v[226:229], v[34:49]
	v_max3_f32 v130, v130, v80, v81
	v_mov_b32_e32 v131, v130
	s_nop 1
	v_permlane32_swap_b32_e32 v130, v131
	v_max_f32_e32 v130, v131, v130
	v_sub_f32_e32 v131, v130, v134
	s_mov_b32 s2, 0x42b504f3
	v_cmp_ge_f32_e32 vcc, s2, v131
	v_max_f32_e32 v130, v134, v130
	s_waitcnt lgkmcnt(0)
	v_mfma_f32_32x32x16_bf16 v[34:49], v[214:217], v[230:233], v[34:49]
	v_sub_f32_e32 v131, v134, v130
	v_mul_f32_e32 v131, 0x3e0293ee, v131
	v_exp_f32_e32 v131, v131
	s_cmp_eq_u64 vcc, exec
	s_cselect_b64 s[2:3], -1, 0
	s_waitcnt vmcnt(4)
	v_cndmask_b32_e64 v214, v131, 1.0, s[2:3]
	v_cmp_gt_f32_e32 vcc, 1.0, v214
	s_waitcnt vmcnt(4)
	ds_write_b128 v177, v[98:101] offset:32768
	ds_write_b128 v208, v[102:105] offset:32768
	s_cbranch_vccz .LBB0_664
	s_and_saveexec_b64 s[4:5], s[0:1]
	ds_write_b32 v149, v214 offset:128
	s_or_b64 exec, exec, s[4:5]
	s_waitcnt lgkmcnt(0)
	v_add_u32_e32 v131, v148, v0
	ds_read_b128 v[136:139], v131 offset:128
	ds_read_b128 v[140:143], v131 offset:160
	ds_read_b128 v[216:219], v131 offset:192
	ds_read_b128 v[220:223], v131 offset:224
	s_waitcnt lgkmcnt(3)
	v_pk_mul_f32 v[50:51], v[136:137], v[50:51]
	v_pk_mul_f32 v[52:53], v[52:53], v[138:139]
	s_waitcnt lgkmcnt(2)
	v_pk_mul_f32 v[54:55], v[54:55], v[140:141]
	v_pk_mul_f32 v[56:57], v[56:57], v[142:143]
	s_waitcnt lgkmcnt(1)
	v_pk_mul_f32 v[58:59], v[58:59], v[216:217]
	v_pk_mul_f32 v[60:61], v[60:61], v[218:219]
	s_waitcnt lgkmcnt(0)
	v_pk_mul_f32 v[62:63], v[62:63], v[220:221]
	v_pk_mul_f32 v[30:31], v[30:31], v[220:221]
	v_pk_mul_f32 v[26:27], v[26:27], v[216:217]
	v_pk_mul_f32 v[22:23], v[22:23], v[140:141]
	v_pk_mul_f32 v[32:33], v[32:33], v[222:223]
	v_pk_mul_f32 v[28:29], v[28:29], v[218:219]
	v_pk_mul_f32 v[24:25], v[24:25], v[142:143]
	v_pk_mul_f32 v[20:21], v[20:21], v[138:139]
	v_pk_mul_f32 v[18:19], v[18:19], v[136:137]
	v_pk_mul_f32 v[64:65], v[64:65], v[222:223]
	v_pk_mul_f32 v[34:35], v[136:137], v[34:35]
	v_pk_mul_f32 v[36:37], v[36:37], v[138:139]
	v_pk_mul_f32 v[38:39], v[38:39], v[140:141]
	v_pk_mul_f32 v[40:41], v[40:41], v[142:143]
	v_pk_mul_f32 v[42:43], v[42:43], v[216:217]
	v_pk_mul_f32 v[44:45], v[44:45], v[218:219]
	v_pk_mul_f32 v[46:47], v[46:47], v[220:221]
	v_pk_mul_f32 v[14:15], v[14:15], v[220:221]
	v_pk_mul_f32 v[10:11], v[10:11], v[216:217]
	v_pk_mul_f32 v[6:7], v[6:7], v[140:141]
	v_pk_mul_f32 v[16:17], v[16:17], v[222:223]
	v_pk_mul_f32 v[12:13], v[12:13], v[218:219]
	v_pk_mul_f32 v[8:9], v[8:9], v[142:143]
	v_pk_mul_f32 v[4:5], v[4:5], v[138:139]
	v_pk_mul_f32 v[2:3], v[2:3], v[136:137]
	v_pk_mul_f32 v[48:49], v[48:49], v[222:223]
; __device__ __forceinline__ void partialSM(f32x16& p0, f32x16& p1, float& m_reg, float& mn, float& alpha, float C, float thrRaw) {
;     ...
;   float mnC = -mn * C;
; #pragma unroll
;   for (int r = 0; r < 16; ++r) p0[r] = fmaf(p0[r], C, mnC);
; #pragma unroll
;   for (int r = 0; r < 16; ++r) p1[r] = fmaf(p1[r], C, mnC);
; #pragma unroll
;   for (int r = 0; r < 16; ++r) p0[r] = __builtin_amdgcn_exp2f(p0[r]);
; }
; __device__ __forceinline__ void finishSM(f32x16& p0, f32x16& p1, float alpha, float& l_reg, bf16x8& pa0, bf16x8& pa1, bf16x8& pa2, bf16x8& pa3) {
; #pragma unroll
;   for (int r = 0; r < 16; ++r) p1[r] = __builtin_amdgcn_exp2f(p1[r]);
;   float ps = 0;
; #pragma unroll
;   for (int r = 0; r < 16; ++r) ps += p0[r];
; #pragma unroll
;   for (int r = 0; r < 16; ++r) ps += p1[r];
;   { auto rr = __builtin_amdgcn_permlane32_swap(__float_as_uint(ps), __float_as_uint(ps), false, false);
;     ps = __uint_as_float(rr[0]) + __uint_as_float(rr[1]); }
;   l_reg = l_reg * alpha + ps;
;     ...
;   PK4(p0, 0, pa0); PK4(p0, 8, pa1); PK4(p1, 0, pa2); PK4(p1, 8, pa3);
;     ...
; }
; template <int DK, bool QL>
; __device__ __forceinline__ void qkt(f32x16& p0, f32x16& p1, const bf16* Ks, const bf16x8* qr, const char* ql, int r32, int hi) {
;   p0 = f32x16{}; p1 = f32x16{};
; #pragma unroll
;   for (int d0 = 0; d0 < DK / 16; ++d0) { int cb = (d0 * 16 + hi * 8) * 2;
;     const bf16x8 qv = QL ? *reinterpret_cast<const bf16x8*>(ql + d0 * 1024) : qr[d0];
;     bf16x8 b0 = *reinterpret_cast<const bf16x8*>((const char*)Ks + kswz<DK>(r32, cb));
;     bf16x8 b1 = *reinterpret_cast<const bf16x8*>((const char*)Ks + kswz<DK>(32 + r32, cb));
;     p0 = __builtin_amdgcn_mfma_f32_32x32x16_bf16(b0, qv, p0, 0, 0, 0);
;     p1 = __builtin_amdgcn_mfma_f32_32x32x16_bf16(b1, qv, p1, 0, 0, 0); }
; }
.LBB0_664:
	v_cndmask_b32_e64 v215, v130, v134, s[2:3]
	v_mul_f32_e32 v216, 0xbe0293ee, v215
	s_mov_b32 s2, 0x3e0293ee
	v_pk_fma_f32 v[82:83], v[82:83], s[2:3], v[216:217] op_sel_hi:[1,0,0]
	v_pk_fma_f32 v[84:85], v[84:85], s[2:3], v[216:217] op_sel_hi:[1,0,0]
	v_pk_fma_f32 v[86:87], v[86:87], s[2:3], v[216:217] op_sel_hi:[1,0,0]
	v_pk_fma_f32 v[88:89], v[88:89], s[2:3], v[216:217] op_sel_hi:[1,0,0]
	v_pk_fma_f32 v[90:91], v[90:91], s[2:3], v[216:217] op_sel_hi:[1,0,0]
	v_pk_fma_f32 v[92:93], v[92:93], s[2:3], v[216:217] op_sel_hi:[1,0,0]
	v_pk_fma_f32 v[94:95], v[94:95], s[2:3], v[216:217] op_sel_hi:[1,0,0]
	v_pk_fma_f32 v[96:97], v[96:97], s[2:3], v[216:217] op_sel_hi:[1,0,0]
	v_exp_f32_e32 v130, v82
	v_exp_f32_e32 v145, v83
	v_exp_f32_e32 v131, v84
	v_exp_f32_e32 v144, v85
	v_exp_f32_e32 v132, v86
	v_exp_f32_e32 v143, v87
	v_exp_f32_e32 v133, v88
	v_exp_f32_e32 v142, v89
	v_exp_f32_e32 v134, v90
	v_exp_f32_e32 v141, v91
	v_exp_f32_e32 v135, v92
	v_exp_f32_e32 v140, v93
	v_exp_f32_e32 v136, v94
	v_exp_f32_e32 v139, v95
	v_exp_f32_e32 v137, v96
	v_exp_f32_e32 v138, v97
	v_fmamk_f32 v218, v71, 0x3e0293ee, v216
	v_fmamk_f32 v217, v78, 0x3e0293ee, v216
	s_add_i32 s8, s8, 2
	v_fmamk_f32 v225, v66, 0x3e0293ee, v216
	v_fmamk_f32 v226, v67, 0x3e0293ee, v216
	v_fmamk_f32 v227, v68, 0x3e0293ee, v216
	v_fmamk_f32 v228, v69, 0x3e0293ee, v216
	v_fmamk_f32 v229, v70, 0x3e0293ee, v216
	v_fmamk_f32 v219, v72, 0x3e0293ee, v216
	v_fmamk_f32 v220, v73, 0x3e0293ee, v216
	v_fmamk_f32 v221, v74, 0x3e0293ee, v216
	v_fmamk_f32 v222, v75, 0x3e0293ee, v216
	v_fmamk_f32 v223, v76, 0x3e0293ee, v216
	v_fmamk_f32 v224, v77, 0x3e0293ee, v216
	v_fmamk_f32 v230, v79, 0x3e0293ee, v216
	v_fmamk_f32 v231, v80, 0x3e0293ee, v216
	v_fmac_f32_e32 v216, 0x3e0293ee, v81
	s_waitcnt lgkmcnt(0)
	s_barrier
	ds_write_b128 v209, v[106:109]
	ds_write_b128 v210, v[110:113]
	ds_read_b128 v[66:69], v153
	ds_read_b128 v[70:73], v159 offset:32768
	ds_read_b128 v[74:77], v159 offset:40960
	ds_read_b128 v[232:235], v153 offset:1024
	ds_read_b128 v[236:239], v207 offset:32768
	ds_read_b128 v[240:243], v207 offset:40960
	v_exp_f32_e32 v174, v219
	v_exp_f32_e32 v219, v221
	s_waitcnt lgkmcnt(4)
	v_mfma_f32_32x32x16_bf16 v[82:97], v[70:73], v[66:69], 0
	v_exp_f32_e32 v221, v223
	v_exp_f32_e32 v223, v217
	v_add_f32_e32 v217, v145, v130
	v_add_f32_e32 v217, v131, v217
	v_add_f32_e32 v217, v144, v217
	v_add_f32_e32 v217, v132, v217
	s_waitcnt lgkmcnt(3)
	v_mfma_f32_32x32x16_bf16 v[66:81], v[74:77], v[66:69], 0
	v_add_f32_e32 v217, v143, v217
	v_add_f32_e32 v217, v133, v217
	v_add_f32_e32 v217, v142, v217
	v_add_f32_e32 v217, v134, v217
	v_add_f32_e32 v217, v141, v217
	v_add_f32_e32 v217, v135, v217
	v_add_f32_e32 v217, v140, v217
	s_waitcnt lgkmcnt(1)
	v_mfma_f32_32x32x16_bf16 v[82:97], v[236:239], v[232:235], v[82:97]
	v_exp_f32_e32 v164, v225
	v_add_f32_e32 v217, v136, v217
	v_exp_f32_e32 v165, v226
	v_add_f32_e32 v217, v139, v217
	v_exp_f32_e32 v166, v227
	v_add_f32_e32 v217, v137, v217
	v_exp_f32_e32 v167, v228
	s_waitcnt lgkmcnt(0)
	v_mfma_f32_32x32x16_bf16 v[66:81], v[240:243], v[232:235], v[66:81]
	ds_read_b128 v[232:235], v153 offset:2048
	ds_read_b128 v[236:239], v161 offset:32768
	ds_read_b128 v[240:243], v161 offset:40960
	v_add_f32_e32 v217, v138, v217
	v_exp_f32_e32 v172, v229
	v_add_f32_e32 v217, v164, v217
	v_exp_f32_e32 v173, v218
	v_add_f32_e32 v217, v165, v217
	v_add_f32_e32 v217, v166, v217
	s_waitcnt lgkmcnt(1)
	v_mfma_f32_32x32x16_bf16 v[82:97], v[236:239], v[232:235], v[82:97]
	v_exp_f32_e32 v175, v220
	v_add_f32_e32 v217, v167, v217
	v_add_f32_e32 v217, v172, v217
	v_exp_f32_e32 v220, v222
	v_add_f32_e32 v217, v173, v217
	v_add_f32_e32 v217, v174, v217
	v_exp_f32_e32 v222, v224
	s_waitcnt lgkmcnt(0)
	v_mfma_f32_32x32x16_bf16 v[66:81], v[240:243], v[232:235], v[66:81]
	ds_read_b128 v[232:235], v153 offset:3072
	ds_read_b128 v[236:239], v160 offset:32768
	ds_read_b128 v[240:243], v160 offset:40960
	v_add_f32_e32 v217, v175, v217
	v_add_f32_e32 v217, v219, v217
	v_exp_f32_e32 v224, v230
	v_add_f32_e32 v217, v220, v217
	v_exp_f32_e32 v225, v231
	v_add_f32_e32 v217, v221, v217
	s_waitcnt lgkmcnt(1)
	v_mfma_f32_32x32x16_bf16 v[82:97], v[236:239], v[232:235], v[82:97]
	v_exp_f32_e32 v216, v216
	v_add_f32_e32 v217, v222, v217
	v_add_f32_e32 v217, v223, v217
	v_add_f32_e32 v217, v224, v217
	v_add_f32_e32 v217, v225, v217
	v_add_f32_e32 v217, v216, v217
	s_waitcnt lgkmcnt(0)
	v_mfma_f32_32x32x16_bf16 v[66:81], v[240:243], v[232:235], v[66:81]
	ds_read_b128 v[232:235], v153 offset:4096
	ds_read_b128 v[236:239], v158 offset:32768
	ds_read_b128 v[240:243], v158 offset:40960
	s_waitcnt lgkmcnt(1)
	v_mfma_f32_32x32x16_bf16 v[82:97], v[236:239], v[232:235], v[82:97]
	s_waitcnt lgkmcnt(0)
	v_mfma_f32_32x32x16_bf16 v[66:81], v[240:243], v[232:235], v[66:81]
	ds_read_b128 v[232:235], v153 offset:5120
	ds_read_b128 v[236:239], v156 offset:32768
	ds_read_b128 v[240:243], v156 offset:40960
	s_waitcnt lgkmcnt(1)
	v_mfma_f32_32x32x16_bf16 v[82:97], v[236:239], v[232:235], v[82:97]
	s_waitcnt lgkmcnt(0)
	v_mfma_f32_32x32x16_bf16 v[66:81], v[240:243], v[232:235], v[66:81]
	ds_read_b128 v[232:235], v153 offset:6144
	ds_read_b128 v[236:239], v157 offset:32768
	ds_read_b128 v[240:243], v157 offset:40960
	s_waitcnt lgkmcnt(1)
	v_mfma_f32_32x32x16_bf16 v[82:97], v[236:239], v[232:235], v[82:97]
	s_waitcnt lgkmcnt(0)
	v_mfma_f32_32x32x16_bf16 v[66:81], v[240:243], v[232:235], v[66:81]
	ds_read_b128 v[232:235], v153 offset:7168
	ds_read_b128 v[236:239], v176 offset:32768
	ds_read_b128 v[240:243], v176 offset:40960
	v_cvt_pk_bf16_f32 v130, v130, v145
	v_cvt_pk_bf16_f32 v131, v131, v144
	v_cvt_pk_bf16_f32 v132, v132, v143
	v_cvt_pk_bf16_f32 v133, v133, v142
	v_cvt_pk_bf16_f32 v134, v134, v141
	v_cvt_pk_bf16_f32 v135, v135, v140
	s_waitcnt lgkmcnt(1)
	v_mfma_f32_32x32x16_bf16 v[82:97], v[236:239], v[232:235], v[82:97]
	v_cvt_pk_bf16_f32 v136, v136, v139
	v_cvt_pk_bf16_f32 v137, v137, v138
	v_cvt_pk_bf16_f32 v138, v164, v165
	v_cvt_pk_bf16_f32 v139, v166, v167
	v_cvt_pk_bf16_f32 v140, v172, v173
	v_cvt_pk_bf16_f32 v141, v174, v175
	v_cvt_pk_bf16_f32 v142, v219, v220
	s_waitcnt lgkmcnt(0)
	v_mfma_f32_32x32x16_bf16 v[66:81], v[240:243], v[232:235], v[66:81]
	v_cvt_pk_bf16_f32 v143, v221, v222
	v_cvt_pk_bf16_f32 v144, v223, v224
	v_cvt_pk_bf16_f32 v145, v225, v216
	s_cmp_gt_u32 s8, 60
	s_cselect_b64 s[4:5], -1, 0
	s_and_b64 vcc, exec, s[4:5]
	s_cbranch_vccnz .Lod_gqa
	v_add_co_u32_e32 v98, vcc, 0xfffb0000, v146
	s_nop 1
	v_addc_co_u32_e32 v99, vcc, -1, v147, vcc
	v_lshl_add_u64 v[164:165], v[98:99], 0, v[178:179]
	global_load_dwordx4 v[106:109], v[164:165], off
	s_nop 0
	global_load_dwordx4 v[98:101], v[98:99], off offset:-512
	s_nop 0
	v_lshl_add_u64 v[166:167], v[146:147], 0, v[178:179]
	global_load_dwordx4 v[110:113], v[166:167], off
	global_load_dwordx4 v[102:105], v[146:147], off offset:-512

; __device__ __forceinline__ void partialSM(f32x16& p0, f32x16& p1, float& m_reg, float& mn, float& alpha, float C, float thrRaw) {
;     ...
;   float mnC = -mn * C;
; #pragma unroll
;   for (int r = 0; r < 16; ++r) p0[r] = fmaf(p0[r], C, mnC);
; #pragma unroll
;   for (int r = 0; r < 16; ++r) p1[r] = fmaf(p1[r], C, mnC);
; #pragma unroll
;   for (int r = 0; r < 16; ++r) p0[r] = __builtin_amdgcn_exp2f(p0[r]);
; }
; __device__ __forceinline__ void finishSM(f32x16& p0, f32x16& p1, float alpha, float& l_reg, bf16x8& pa0, bf16x8& pa1, bf16x8& pa2, bf16x8& pa3) {
; #pragma unroll
;   for (int r = 0; r < 16; ++r) p1[r] = __builtin_amdgcn_exp2f(p1[r]);
;   float ps = 0;
; #pragma unroll
;   for (int r = 0; r < 16; ++r) ps += p0[r];
; #pragma unroll
;   for (int r = 0; r < 16; ++r) ps += p1[r];
;   { auto rr = __builtin_amdgcn_permlane32_swap(__float_as_uint(ps), __float_as_uint(ps), false, false);
;     ps = __uint_as_float(rr[0]) + __uint_as_float(rr[1]); }
;   l_reg = l_reg * alpha + ps;
.LBB0_670:
	v_cndmask_b32_e64 v134, v131, v215, s[2:3]
	v_mul_f32_e32 v120, 0xbe0293ee, v134
	v_mov_b32_e32 v121, v120
	s_mov_b32 s2, 0x3e0293ee
	v_pk_fma_f32 v[82:83], v[82:83], s[2:3], v[120:121] op_sel_hi:[1,0,0]
	v_pk_fma_f32 v[84:85], v[84:85], s[2:3], v[120:121] op_sel_hi:[1,0,0]
	v_pk_fma_f32 v[86:87], v[86:87], s[2:3], v[120:121] op_sel_hi:[1,0,0]
	v_pk_fma_f32 v[88:89], v[88:89], s[2:3], v[120:121] op_sel_hi:[1,0,0]
	v_pk_fma_f32 v[90:91], v[90:91], s[2:3], v[120:121] op_sel_hi:[1,0,0]
	v_pk_fma_f32 v[92:93], v[92:93], s[2:3], v[120:121] op_sel_hi:[1,0,0]
	v_pk_fma_f32 v[94:95], v[94:95], s[2:3], v[120:121] op_sel_hi:[1,0,0]
	v_fmamk_f32 v96, v96, 0x3e0293ee, v120
	v_fmac_f32_e32 v121, 0x3e0293ee, v97
	s_mov_b32 s2, 0x3e0293ee
	v_exp_f32_e32 v145, v82
	v_exp_f32_e32 v216, v83
	v_exp_f32_e32 v131, v84
	v_exp_f32_e32 v215, v85
	v_exp_f32_e32 v132, v86
	v_exp_f32_e32 v144, v87
	v_exp_f32_e32 v133, v88
	v_exp_f32_e32 v143, v89
	v_exp_f32_e32 v140, v90
	v_exp_f32_e32 v142, v91
	v_exp_f32_e32 v139, v92
	v_exp_f32_e32 v141, v93
	v_exp_f32_e32 v136, v94
	v_exp_f32_e32 v138, v95
	v_exp_f32_e32 v135, v96
	v_exp_f32_e32 v137, v121
	v_pk_fma_f32 v[126:127], v[66:67], s[2:3], v[120:121] op_sel_hi:[1,0,0]
	v_pk_fma_f32 v[124:125], v[68:69], s[2:3], v[120:121] op_sel_hi:[1,0,0]
	v_pk_fma_f32 v[118:119], v[70:71], s[2:3], v[120:121] op_sel_hi:[1,0,0]
	v_pk_fma_f32 v[116:117], v[72:73], s[2:3], v[120:121] op_sel_hi:[1,0,0]
	v_pk_fma_f32 v[114:115], v[74:75], s[2:3], v[120:121] op_sel_hi:[1,0,0]
	v_pk_fma_f32 v[128:129], v[76:77], s[2:3], v[120:121] op_sel_hi:[1,0,0]
	v_pk_fma_f32 v[122:123], v[78:79], s[2:3], v[120:121] op_sel_hi:[1,0,0]
	v_pk_fma_f32 v[120:121], v[80:81], s[2:3], v[120:121] op_sel_hi:[1,0,0]
	v_fma_f32 v66, v211, v150, v212
	s_mov_b64 s[2:3], 0x140000
	v_fma_f32 v150, v66, v214, v217
	v_lshl_add_u64 v[146:147], v[146:147], 0, s[2:3]
	s_and_b64 vcc, exec, s[4:5]
	s_waitcnt lgkmcnt(0)
	s_barrier
	s_cbranch_vccnz .LBB0_672
	v_mov_b32_e32 v211, v130
	ds_write_b128 v209, v[244:247] offset:16384
	ds_write_b128 v210, v[194:197] offset:16384
	s_branch .LBB0_660

; #define SBAR() __builtin_amdgcn_sched_barrier(0)
; #define HOOK(P0, P1, j) do { if (NA) na_hook(P0, P1, krow0 + (j), q_row, q_col, win_r, win_c, rpb, inv_scale, hi); } while (0)
; __device__ __forceinline__ void finishSM(f32x16& p0, f32x16& p1, float alpha, float& l_reg, bf16x8& pa0, bf16x8& pa1, bf16x8& pa2, bf16x8& pa3) {
; #pragma unroll
;   for (int r = 0; r < 16; ++r) p1[r] = __builtin_amdgcn_exp2f(p1[r]);
;   float ps = 0;
; #pragma unroll
;   for (int r = 0; r < 16; ++r) ps += p0[r];
; #pragma unroll
;   for (int r = 0; r < 16; ++r) ps += p1[r];
;   { auto rr = __builtin_amdgcn_permlane32_swap(__float_as_uint(ps), __float_as_uint(ps), false, false);
;     ps = __uint_as_float(rr[0]) + __uint_as_float(rr[1]); }
;   l_reg = l_reg * alpha + ps;
;     ...
;   PK4(p0, 0, pa0); PK4(p0, 8, pa1); PK4(p1, 0, pa2); PK4(p1, 8, pa3);
;     ...
; }
; template <int DK, bool QL>
; __device__ __forceinline__ void qkt(f32x16& p0, f32x16& p1, const bf16* Ks, const bf16x8* qr, const char* ql, int r32, int hi) {
;   p0 = f32x16{}; p1 = f32x16{};
; #pragma unroll
;   for (int d0 = 0; d0 < DK / 16; ++d0) { int cb = (d0 * 16 + hi * 8) * 2;
;     const bf16x8 qv = QL ? *reinterpret_cast<const bf16x8*>(ql + d0 * 1024) : qr[d0];
;     bf16x8 b0 = *reinterpret_cast<const bf16x8*>((const char*)Ks + kswz<DK>(r32, cb));
;     bf16x8 b1 = *reinterpret_cast<const bf16x8*>((const char*)Ks + kswz<DK>(32 + r32, cb));
;     p0 = __builtin_amdgcn_mfma_f32_32x32x16_bf16(b0, qv, p0, 0, 0, 0);
;     p1 = __builtin_amdgcn_mfma_f32_32x32x16_bf16(b1, qv, p1, 0, 0, 0); }
; }
; template <int DK, bool NA, bool QL, int SD> ...
;     ...
;   SBAR(); qkt<DK, QL>(pB0, pB1, (bf16*)((char*)K_lds + SHM_K), qr, ql, r32, hi); HOOK(pB0, pB1, NT - 1);
;   finishSM(pA0, pA1, alA, l_reg, pa0, pa1, pa2, pa3); SBAR();
;   pv_d0(o, vb0, pa0, pa1, pa2, pa3); partialSM(pB0, pB1, m_reg, mnB, alB, C, thrRaw);
.LBB0_672:
	v_mov_b32_e32 v213, v150
	s_nop 1
	v_permlane32_swap_b32_e32 v150, v213
	v_add_f32_e32 v150, v150, v213
	ds_write_b128 v209, v[244:247] offset:16384
	ds_write_b128 v210, v[194:197] offset:16384
	ds_read_b128 v[66:69], v153
	ds_read_b128 v[70:73], v159 offset:49152
	ds_read_b128 v[74:77], v159 offset:57344
	ds_read_b128 v[98:101], v153 offset:1024
	ds_read_b128 v[102:105], v207 offset:49152
	ds_read_b128 v[106:109], v207 offset:57344
	v_exp_f32_e32 v110, v124
	v_exp_f32_e32 v111, v125
	s_waitcnt lgkmcnt(4)
	v_mfma_f32_32x32x16_bf16 v[82:97], v[70:73], v[66:69], 0
	v_exp_f32_e32 v112, v118
	v_exp_f32_e32 v113, v119
	v_exp_f32_e32 v116, v116
	v_exp_f32_e32 v117, v117
	v_exp_f32_e32 v114, v114
	v_exp_f32_e32 v115, v115
	v_exp_f32_e32 v118, v128
	s_waitcnt lgkmcnt(3)
	v_mfma_f32_32x32x16_bf16 v[66:81], v[74:77], v[66:69], 0
	v_exp_f32_e32 v119, v129
	v_exp_f32_e32 v122, v122
	v_exp_f32_e32 v123, v123
	v_exp_f32_e32 v120, v120
	v_exp_f32_e32 v121, v121
	s_waitcnt lgkmcnt(1)
	v_mfma_f32_32x32x16_bf16 v[82:97], v[102:105], v[98:101], v[82:97]
	s_waitcnt lgkmcnt(0)
	v_mfma_f32_32x32x16_bf16 v[66:81], v[106:109], v[98:101], v[66:81]
	ds_read_b128 v[98:101], v153 offset:2048
	ds_read_b128 v[102:105], v161 offset:49152
	ds_read_b128 v[106:109], v161 offset:57344
	s_waitcnt lgkmcnt(1)
	v_mfma_f32_32x32x16_bf16 v[82:97], v[102:105], v[98:101], v[82:97]
	s_waitcnt lgkmcnt(0)
	v_mfma_f32_32x32x16_bf16 v[66:81], v[106:109], v[98:101], v[66:81]
	ds_read_b128 v[98:101], v153 offset:3072
	ds_read_b128 v[102:105], v160 offset:49152
	ds_read_b128 v[106:109], v160 offset:57344
	s_waitcnt lgkmcnt(1)
	v_mfma_f32_32x32x16_bf16 v[82:97], v[102:105], v[98:101], v[82:97]
	s_waitcnt lgkmcnt(0)
	v_mfma_f32_32x32x16_bf16 v[66:81], v[106:109], v[98:101], v[66:81]
	ds_read_b128 v[98:101], v153 offset:4096
	ds_read_b128 v[102:105], v158 offset:49152
	ds_read_b128 v[106:109], v158 offset:57344
	s_waitcnt lgkmcnt(1)
	v_mfma_f32_32x32x16_bf16 v[82:97], v[102:105], v[98:101], v[82:97]
	s_waitcnt lgkmcnt(0)
	v_mfma_f32_32x32x16_bf16 v[66:81], v[106:109], v[98:101], v[66:81]
	ds_read_b128 v[98:101], v153 offset:5120
	ds_read_b128 v[102:105], v156 offset:49152
	ds_read_b128 v[106:109], v156 offset:57344
	s_waitcnt lgkmcnt(1)
	v_mfma_f32_32x32x16_bf16 v[82:97], v[102:105], v[98:101], v[82:97]
	s_waitcnt lgkmcnt(0)
	v_mfma_f32_32x32x16_bf16 v[66:81], v[106:109], v[98:101], v[66:81]
	ds_read_b128 v[98:101], v153 offset:6144
	ds_read_b128 v[102:105], v157 offset:49152
	ds_read_b128 v[106:109], v157 offset:57344
	s_waitcnt lgkmcnt(1)
	v_mfma_f32_32x32x16_bf16 v[82:97], v[102:105], v[98:101], v[82:97]
	s_waitcnt lgkmcnt(0)
	v_mfma_f32_32x32x16_bf16 v[66:81], v[106:109], v[98:101], v[66:81]
	ds_read_b128 v[98:101], v153 offset:7168
	ds_read_b128 v[102:105], v176 offset:49152
	ds_read_b128 v[106:109], v176 offset:57344
	s_waitcnt lgkmcnt(1)
	v_mfma_f32_32x32x16_bf16 v[82:97], v[102:105], v[98:101], v[82:97]
	s_waitcnt lgkmcnt(0)
	v_mfma_f32_32x32x16_bf16 v[66:81], v[106:109], v[98:101], v[66:81]
	v_add_f32_e32 v98, 0, v145
	v_add_f32_e32 v98, v216, v98
	v_add_f32_e32 v98, v131, v98
	v_add_f32_e32 v98, v215, v98
	v_add_f32_e32 v98, v132, v98
	v_add_f32_e32 v98, v144, v98
	v_add_f32_e32 v98, v133, v98
	v_add_f32_e32 v98, v143, v98
	v_add_f32_e32 v98, v140, v98
	v_add_f32_e32 v98, v142, v98
	v_add_f32_e32 v98, v139, v98
	v_add_f32_e32 v98, v141, v98
	v_exp_f32_e32 v108, v126
	v_add_f32_e32 v98, v136, v98
	v_exp_f32_e32 v109, v127
	v_add_f32_e32 v98, v138, v98
	v_add_f32_e32 v98, v135, v98
	v_add_f32_e32 v98, v137, v98
	v_add_f32_e32 v98, v108, v98
	v_add_f32_e32 v98, v109, v98
	v_add_f32_e32 v98, v110, v98
	v_add_f32_e32 v98, v111, v98
	v_add_f32_e32 v98, v112, v98
	v_add_f32_e32 v98, v113, v98
	v_add_f32_e32 v98, v116, v98
	v_add_f32_e32 v98, v117, v98
	v_add_f32_e32 v98, v114, v98
	v_add_f32_e32 v98, v115, v98
	v_add_f32_e32 v98, v118, v98
	v_add_f32_e32 v98, v119, v98
	v_add_f32_e32 v98, v122, v98
	v_add_f32_e32 v98, v123, v98
	v_add_f32_e32 v98, v120, v98
	v_add_f32_e32 v102, v121, v98
	v_mov_b32_e32 v103, v102
	v_cvt_pk_bf16_f32 v98, v145, v216
	v_cvt_pk_bf16_f32 v99, v131, v215
	v_cvt_pk_bf16_f32 v100, v132, v144
	v_cvt_pk_bf16_f32 v101, v133, v143
	s_nop 1
	v_permlane32_swap_b32_e32 v102, v103
	v_cvt_pk_bf16_f32 v104, v140, v142
	v_cvt_pk_bf16_f32 v105, v139, v141
	v_cvt_pk_bf16_f32 v106, v136, v138
	v_cvt_pk_bf16_f32 v107, v135, v137
	v_cvt_pk_bf16_f32 v108, v108, v109
	v_cvt_pk_bf16_f32 v109, v110, v111
	v_cvt_pk_bf16_f32 v110, v112, v113
	v_cvt_pk_bf16_f32 v111, v116, v117
	v_cvt_pk_bf16_f32 v112, v114, v115
	v_cvt_pk_bf16_f32 v113, v118, v119
	v_cvt_pk_bf16_f32 v114, v122, v123
	v_cvt_pk_bf16_f32 v115, v120, v121
	s_nop 0
	ds_read_b64_tr_b16 v[116:117], v152 offset:0
	ds_read_b64_tr_b16 v[118:119], v152 offset:0x800
	ds_read_b64_tr_b16 v[120:121], v152 offset:0x1000
	ds_read_b64_tr_b16 v[122:123], v152 offset:0x1800
	ds_read_b64_tr_b16 v[124:125], v152 offset:0x2000
	ds_read_b64_tr_b16 v[126:127], v152 offset:0x2800
	ds_read_b64_tr_b16 v[136:137], v152 offset:0x3000
	ds_read_b64_tr_b16 v[138:139], v152 offset:0x3800
	s_waitcnt lgkmcnt(0)
; #define SBAR() __builtin_amdgcn_sched_barrier(0)
; __device__ __forceinline__ void partialSM(f32x16& p0, f32x16& p1, float& m_reg, float& mn, float& alpha, float C, float thrRaw) {
;   float pmax = p0[0];
; #pragma unroll
;   for (int r = 1; r < 16; ++r) pmax = fmaxf(pmax, p0[r]);
; #pragma unroll
;   for (int r = 0; r < 16; ++r) pmax = fmaxf(pmax, p1[r]);
;   { auto rr = __builtin_amdgcn_permlane32_swap(__float_as_uint(pmax), __float_as_uint(pmax), false, false);
;     pmax = fmaxf(__uint_as_float(rr[0]), __uint_as_float(rr[1])); }
;   if (__builtin_expect(__all(pmax - m_reg <= thrRaw), 1)) { mn = m_reg; alpha = 1.f; }
;   else { mn = fmaxf(m_reg, pmax); alpha = __builtin_amdgcn_exp2f((m_reg - mn) * C); m_reg = mn; }
; template <int D0> __device__ __forceinline__ void pv_one(f32x16& od, int vb, bf16x8 pa0, bf16x8 pa1, bf16x8 pa2, bf16x8 pa3) {
;   const s16x4 l0 = tr_read<v_rd_off(D0, 0, 0)>(vb), h0 = tr_read<v_rd_off(D0, 0, 1)>(vb), l1 = tr_read<v_rd_off(D0, 1, 0)>(vb), h1 = tr_read<v_rd_off(D0, 1, 1)>(vb);
;   const s16x4 l2 = tr_read<v_rd_off(D0, 2, 0)>(vb), h2 = tr_read<v_rd_off(D0, 2, 1)>(vb), l3 = tr_read<v_rd_off(D0, 3, 0)>(vb), h3 = tr_read<v_rd_off(D0, 3, 1)>(vb);
;   asm volatile("s_waitcnt lgkmcnt(0)" ::: "memory"); SBAR();
;     ...
;   od = __builtin_amdgcn_mfma_f32_32x32x16_bf16(pa0, PK(l0, h0), od, 0, 0, 0);
;   od = __builtin_amdgcn_mfma_f32_32x32x16_bf16(pa1, PK(l1, h1), od, 0, 0, 0);
;   od = __builtin_amdgcn_mfma_f32_32x32x16_bf16(pa2, PK(l2, h2), od, 0, 0, 0);
;   od = __builtin_amdgcn_mfma_f32_32x32x16_bf16(pa3, PK(l3, h3), od, 0, 0, 0);
;     ...
; }
; __device__ __forceinline__ void pv_d0(f32x16* o, int vb, bf16x8 pa0, bf16x8 pa1, bf16x8 pa2, bf16x8 pa3) {
;   pv_one<0>(o[0], vb, pa0, pa1, pa2, pa3); pv_one<1>(o[1], vb, pa0, pa1, pa2, pa3); pv_one<2>(o[2], vb, pa0, pa1, pa2, pa3); pv_one<3>(o[3], vb, pa0, pa1, pa2, pa3);
	s_nop 0
	v_mfma_f32_32x32x16_bf16 v[18:33], v[98:101], v[116:119], v[18:33]
	ds_read_b64_tr_b16 v[116:117], v152 offset:0x200
	ds_read_b64_tr_b16 v[118:119], v152 offset:0xa00
	v_mfma_f32_32x32x16_bf16 v[18:33], v[104:107], v[120:123], v[18:33]
	ds_read_b64_tr_b16 v[120:121], v152 offset:0x1200
	ds_read_b64_tr_b16 v[122:123], v152 offset:0x1a00
	v_mfma_f32_32x32x16_bf16 v[18:33], v[108:111], v[124:127], v[18:33]
	ds_read_b64_tr_b16 v[124:125], v152 offset:0x2200
	ds_read_b64_tr_b16 v[126:127], v152 offset:0x2a00
	v_mfma_f32_32x32x16_bf16 v[18:33], v[112:115], v[136:139], v[18:33]
	ds_read_b64_tr_b16 v[136:137], v152 offset:0x3200
	ds_read_b64_tr_b16 v[138:139], v152 offset:0x3a00
	s_waitcnt lgkmcnt(0)
	v_mfma_f32_32x32x16_bf16 v[50:65], v[98:101], v[116:119], v[50:65]
	ds_read_b64_tr_b16 v[116:117], v152 offset:0x400
	ds_read_b64_tr_b16 v[118:119], v152 offset:0xc00
	v_mfma_f32_32x32x16_bf16 v[50:65], v[104:107], v[120:123], v[50:65]
	ds_read_b64_tr_b16 v[120:121], v152 offset:0x1400
	ds_read_b64_tr_b16 v[122:123], v152 offset:0x1c00
	v_mfma_f32_32x32x16_bf16 v[50:65], v[108:111], v[124:127], v[50:65]
	ds_read_b64_tr_b16 v[124:125], v152 offset:0x2400
	ds_read_b64_tr_b16 v[126:127], v152 offset:0x2c00
	v_mfma_f32_32x32x16_bf16 v[50:65], v[112:115], v[136:139], v[50:65]
	ds_read_b64_tr_b16 v[136:137], v152 offset:0x3400
	ds_read_b64_tr_b16 v[138:139], v152 offset:0x3c00
	s_waitcnt lgkmcnt(0)
	v_mfma_f32_32x32x16_bf16 v[2:17], v[98:101], v[116:119], v[2:17]
	ds_read_b64_tr_b16 v[116:117], v152 offset:0x600
	ds_read_b64_tr_b16 v[118:119], v152 offset:0xe00
	v_mfma_f32_32x32x16_bf16 v[2:17], v[104:107], v[120:123], v[2:17]
	ds_read_b64_tr_b16 v[120:121], v152 offset:0x1600
	ds_read_b64_tr_b16 v[122:123], v152 offset:0x1e00
	v_mfma_f32_32x32x16_bf16 v[2:17], v[108:111], v[124:127], v[2:17]
	ds_read_b64_tr_b16 v[124:125], v152 offset:0x2600
	ds_read_b64_tr_b16 v[126:127], v152 offset:0x2e00
	v_mfma_f32_32x32x16_bf16 v[2:17], v[112:115], v[136:139], v[2:17]
	ds_read_b64_tr_b16 v[136:137], v152 offset:0x3600
	ds_read_b64_tr_b16 v[138:139], v152 offset:0x3e00
	s_waitcnt lgkmcnt(0)
	v_mfma_f32_32x32x16_bf16 v[34:49], v[98:101], v[116:119], v[34:49]
	v_max_f32_e32 v98, v83, v83
	v_max_f32_e32 v99, v82, v82
	v_max_f32_e32 v98, v99, v98
	v_max3_f32 v98, v98, v84, v85
	v_max3_f32 v98, v98, v86, v87
	v_max3_f32 v98, v98, v88, v89
	v_max3_f32 v98, v98, v90, v91
	v_max3_f32 v98, v98, v92, v93
	v_max3_f32 v98, v98, v94, v95
	v_mfma_f32_32x32x16_bf16 v[34:49], v[104:107], v[120:123], v[34:49]
	v_max3_f32 v98, v98, v96, v97
	v_max3_f32 v98, v98, v66, v67
	v_max3_f32 v98, v98, v68, v69
	v_max3_f32 v98, v98, v70, v71
	v_max3_f32 v98, v98, v72, v73
	v_max3_f32 v98, v98, v74, v75
	v_max3_f32 v98, v98, v76, v77
	v_max3_f32 v98, v98, v78, v79
	v_mfma_f32_32x32x16_bf16 v[34:49], v[108:111], v[124:127], v[34:49]
	v_max3_f32 v98, v98, v80, v81
	v_mov_b32_e32 v99, v98
	s_nop 1
	v_permlane32_swap_b32_e32 v98, v99
	v_max_f32_e32 v99, v99, v99
	v_max_f32_e32 v98, v98, v98
	v_max_f32_e32 v98, v98, v99
	v_sub_f32_e32 v99, v98, v134
	s_mov_b32 s2, 0x42b504f3
	v_cmp_ge_f32_e32 vcc, s2, v99
	v_max_f32_e32 v99, v134, v134
	v_max_f32_e32 v99, v99, v98
	v_mfma_f32_32x32x16_bf16 v[34:49], v[112:115], v[136:139], v[34:49]
	v_sub_f32_e32 v98, v134, v99
	v_mul_f32_e32 v98, 0x3e0293ee, v98
	v_exp_f32_e32 v98, v98
	s_cmp_eq_u64 vcc, exec
	s_cselect_b64 s[2:3], -1, 0
	v_cndmask_b32_e64 v98, v98, 1.0, s[2:3]
	v_cmp_gt_f32_e32 vcc, 1.0, v98
	s_barrier
	s_cbranch_vccz .LBB0_676
	s_and_saveexec_b64 s[4:5], s[0:1]
	ds_write_b32 v149, v98 offset:128
	s_or_b64 exec, exec, s[4:5]
	s_waitcnt lgkmcnt(0)
	v_add_u32_e32 v100, v148, v0
	ds_read_b128 v[104:107], v100 offset:128
	ds_read_b128 v[108:111], v100 offset:160
	ds_read_b128 v[112:115], v100 offset:192
	ds_read_b128 v[116:119], v100 offset:224
	s_waitcnt lgkmcnt(3)
	v_pk_mul_f32 v[50:51], v[104:105], v[50:51]
	v_pk_mul_f32 v[52:53], v[52:53], v[106:107]
	s_waitcnt lgkmcnt(2)
	v_pk_mul_f32 v[54:55], v[54:55], v[108:109]
	v_pk_mul_f32 v[56:57], v[56:57], v[110:111]
	s_waitcnt lgkmcnt(1)
	v_pk_mul_f32 v[58:59], v[58:59], v[112:113]
	v_pk_mul_f32 v[60:61], v[60:61], v[114:115]
	s_waitcnt lgkmcnt(0)
	v_pk_mul_f32 v[62:63], v[62:63], v[116:117]
	v_pk_mul_f32 v[30:31], v[30:31], v[116:117]
	v_pk_mul_f32 v[26:27], v[26:27], v[112:113]
	v_pk_mul_f32 v[22:23], v[22:23], v[108:109]
	v_pk_mul_f32 v[32:33], v[32:33], v[118:119]
	v_pk_mul_f32 v[28:29], v[28:29], v[114:115]
	v_pk_mul_f32 v[24:25], v[24:25], v[110:111]
	v_pk_mul_f32 v[20:21], v[20:21], v[106:107]
	v_pk_mul_f32 v[18:19], v[18:19], v[104:105]
	v_pk_mul_f32 v[64:65], v[64:65], v[118:119]
	v_pk_mul_f32 v[34:35], v[104:105], v[34:35]
	v_pk_mul_f32 v[36:37], v[36:37], v[106:107]
	v_pk_mul_f32 v[38:39], v[38:39], v[108:109]
	v_pk_mul_f32 v[40:41], v[40:41], v[110:111]
	v_pk_mul_f32 v[42:43], v[42:43], v[112:113]
	v_pk_mul_f32 v[44:45], v[44:45], v[114:115]
	v_pk_mul_f32 v[46:47], v[46:47], v[116:117]
	v_pk_mul_f32 v[14:15], v[14:15], v[116:117]
	v_pk_mul_f32 v[10:11], v[10:11], v[112:113]
	v_pk_mul_f32 v[6:7], v[6:7], v[108:109]
	v_pk_mul_f32 v[16:17], v[16:17], v[118:119]
	v_pk_mul_f32 v[12:13], v[12:13], v[114:115]
	v_pk_mul_f32 v[8:9], v[8:9], v[110:111]
	v_pk_mul_f32 v[4:5], v[4:5], v[106:107]
	v_pk_mul_f32 v[2:3], v[2:3], v[104:105]
	v_pk_mul_f32 v[48:49], v[48:49], v[118:119]

; #define SBAR() __builtin_amdgcn_sched_barrier(0)
; __device__ __forceinline__ void finishSM(f32x16& p0, f32x16& p1, float alpha, float& l_reg, bf16x8& pa0, bf16x8& pa1, bf16x8& pa2, bf16x8& pa3) {
; #pragma unroll
;   for (int r = 0; r < 16; ++r) p1[r] = __builtin_amdgcn_exp2f(p1[r]);
;   float ps = 0;
; #pragma unroll
;   for (int r = 0; r < 16; ++r) ps += p0[r];
; #pragma unroll
;   for (int r = 0; r < 16; ++r) ps += p1[r];
;   { auto rr = __builtin_amdgcn_permlane32_swap(__float_as_uint(ps), __float_as_uint(ps), false, false);
;     ps = __uint_as_float(rr[0]) + __uint_as_float(rr[1]); }
;   l_reg = l_reg * alpha + ps;
;     ...
;   PK4(p0, 0, pa0); PK4(p0, 8, pa1); PK4(p1, 0, pa2); PK4(p1, 8, pa3);
;     ...
; }
; template <int DK, bool QL>
; __device__ __forceinline__ void qkt(f32x16& p0, f32x16& p1, const bf16* Ks, const bf16x8* qr, const char* ql, int r32, int hi) {
;   p0 = f32x16{}; p1 = f32x16{};
; #pragma unroll
;   for (int d0 = 0; d0 < DK / 16; ++d0) { int cb = (d0 * 16 + hi * 8) * 2;
;     const bf16x8 qv = QL ? *reinterpret_cast<const bf16x8*>(ql + d0 * 1024) : qr[d0];
;     bf16x8 b0 = *reinterpret_cast<const bf16x8*>((const char*)Ks + kswz<DK>(r32, cb));
;     bf16x8 b1 = *reinterpret_cast<const bf16x8*>((const char*)Ks + kswz<DK>(32 + r32, cb));
;     p0 = __builtin_amdgcn_mfma_f32_32x32x16_bf16(b0, qv, p0, 0, 0, 0);
;     p1 = __builtin_amdgcn_mfma_f32_32x32x16_bf16(b1, qv, p1, 0, 0, 0); }
; }
; template <int OFF> __device__ __forceinline__ s16x4 tr_read(int vb) {
;   s16x4 r; asm volatile("ds_read_b64_tr_b16 %0, %1 offset:%2" : "=&v"(r) : "v"(vb), "i"(OFF) : "memory"); return r;
; }
; template <int D0> __device__ __forceinline__ void pv_one(f32x16& od, int vb, bf16x8 pa0, bf16x8 pa1, bf16x8 pa2, bf16x8 pa3) {
;   const s16x4 l0 = tr_read<v_rd_off(D0, 0, 0)>(vb), h0 = tr_read<v_rd_off(D0, 0, 1)>(vb), l1 = tr_read<v_rd_off(D0, 1, 0)>(vb), h1 = tr_read<v_rd_off(D0, 1, 1)>(vb);
;   const s16x4 l2 = tr_read<v_rd_off(D0, 2, 0)>(vb), h2 = tr_read<v_rd_off(D0, 2, 1)>(vb), l3 = tr_read<v_rd_off(D0, 3, 0)>(vb), h3 = tr_read<v_rd_off(D0, 3, 1)>(vb);
;   asm volatile("s_waitcnt lgkmcnt(0)" ::: "memory"); SBAR();
;     ...
;   od = __builtin_amdgcn_mfma_f32_32x32x16_bf16(pa0, PK(l0, h0), od, 0, 0, 0);
;   od = __builtin_amdgcn_mfma_f32_32x32x16_bf16(pa1, PK(l1, h1), od, 0, 0, 0);
;   od = __builtin_amdgcn_mfma_f32_32x32x16_bf16(pa2, PK(l2, h2), od, 0, 0, 0);
.LBB0_682:
	ds_read_b128 v[66:69], v212 offset:49152
	ds_read_b128 v[70:73], v212 offset:53248
	v_exp_f32_e32 v143, v138
	v_add_f32_e32 v138, v226, v177
	s_waitcnt lgkmcnt(1)
	v_mfma_f32_32x32x16_bf16 v[82:97], v[66:69], v[110:113], 0
	v_add_f32_e32 v138, v161, v138
	v_add_f32_e32 v138, v223, v138
	v_add_f32_e32 v138, v153, v138
	ds_read_b128 v[228:231], v216 offset:49152
	ds_read_b128 v[232:235], v216 offset:53248
	v_add_f32_e32 v138, v176, v138
	v_add_f32_e32 v138, v152, v138
	v_add_f32_e32 v138, v160, v138
	s_waitcnt lgkmcnt(2)
	v_mfma_f32_32x32x16_bf16 v[66:81], v[70:73], v[110:113], 0
	v_add_f32_e32 v138, v149, v138
	v_add_f32_e32 v138, v151, v138
	v_add_f32_e32 v138, v147, v138
	v_add_f32_e32 v138, v150, v138
	v_add_f32_e32 v138, v145, v138
	v_exp_f32_e32 v164, v139
	v_add_f32_e32 v138, v148, v138
	s_waitcnt lgkmcnt(1)
	v_mfma_f32_32x32x16_bf16 v[82:97], v[228:231], v[106:109], v[82:97]
	v_exp_f32_e32 v136, v136
	v_add_f32_e32 v138, v144, v138
	v_exp_f32_e32 v137, v137
	v_add_f32_e32 v138, v146, v138
	v_exp_f32_e32 v130, v130
	v_add_f32_e32 v138, v143, v138
	v_exp_f32_e32 v131, v131
	s_waitcnt lgkmcnt(0)
	v_mfma_f32_32x32x16_bf16 v[66:81], v[232:235], v[106:109], v[66:81]
	ds_read_b128 v[228:231], v217 offset:49152
	ds_read_b128 v[232:235], v217 offset:53248
	v_add_f32_e32 v138, v164, v138
	v_exp_f32_e32 v128, v128
	v_add_f32_e32 v138, v136, v138
	v_exp_f32_e32 v129, v129
	v_add_f32_e32 v138, v137, v138
	v_exp_f32_e32 v126, v126
	s_waitcnt lgkmcnt(1)
	v_mfma_f32_32x32x16_bf16 v[82:97], v[228:231], v[98:101], v[82:97]
	v_add_f32_e32 v138, v130, v138
	v_exp_f32_e32 v127, v127
	v_add_f32_e32 v138, v131, v138
	v_exp_f32_e32 v165, v140
	v_add_f32_e32 v138, v128, v138
	v_exp_f32_e32 v166, v141
	v_add_f32_e32 v138, v129, v138
	s_waitcnt lgkmcnt(0)
	v_mfma_f32_32x32x16_bf16 v[66:81], v[232:235], v[98:101], v[66:81]
	ds_read_b128 v[228:231], v218 offset:49152
	ds_read_b128 v[232:235], v218 offset:53248
	v_exp_f32_e32 v134, v134
	v_add_f32_e32 v138, v126, v138
	v_exp_f32_e32 v135, v135
	v_add_f32_e32 v138, v127, v138
	v_exp_f32_e32 v132, v132
	v_add_f32_e32 v138, v165, v138
	s_waitcnt lgkmcnt(1)
	v_mfma_f32_32x32x16_bf16 v[82:97], v[228:231], v[102:105], v[82:97]
	v_exp_f32_e32 v133, v133
	v_add_f32_e32 v138, v166, v138
	v_add_f32_e32 v138, v134, v138
	v_add_f32_e32 v138, v135, v138
	v_add_f32_e32 v138, v132, v138
	v_add_f32_e32 v220, v133, v138
	s_waitcnt lgkmcnt(0)
	v_mfma_f32_32x32x16_bf16 v[66:81], v[232:235], v[102:105], v[66:81]
	v_cvt_pk_bf16_f32 v138, v177, v226
	v_cvt_pk_bf16_f32 v139, v161, v223
	v_cvt_pk_bf16_f32 v140, v153, v176
	v_cvt_pk_bf16_f32 v141, v152, v160
	v_cvt_pk_bf16_f32 v222, v149, v151
	v_cvt_pk_bf16_f32 v223, v147, v150
	v_cvt_pk_bf16_f32 v224, v145, v148
	v_cvt_pk_bf16_f32 v225, v144, v146
	v_cvt_pk_bf16_f32 v144, v143, v164
	v_cvt_pk_bf16_f32 v145, v136, v137
	v_cvt_pk_bf16_f32 v146, v130, v131
	v_cvt_pk_bf16_f32 v147, v128, v129
	v_cvt_pk_bf16_f32 v148, v126, v127
	v_cvt_pk_bf16_f32 v149, v165, v166
	v_cvt_pk_bf16_f32 v150, v134, v135
	v_cvt_pk_bf16_f32 v151, v132, v133
	global_load_dwordx4 v[182:185], v[178:179], off offset:2048
	global_load_dwordx4 v[194:197], v[180:181], off offset:2048
	global_load_dwordx4 v[134:137], v[204:205], off offset:1024
	s_mov_b32 s4, 0xa0000
	s_mov_b32 s5, 0
	s_nop 0
	v_lshl_add_u64 v[178:179], v[178:179], 0, s[4:5]
	v_lshl_add_u64 v[180:181], v[180:181], 0, s[4:5]
	v_lshl_add_u64 v[204:205], v[204:205], 0, s[4:5]
	ds_read_b64_tr_b16 v[226:227], v211 offset:0
	ds_read_b64_tr_b16 v[228:229], v211 offset:0x800
	ds_read_b64_tr_b16 v[230:231], v211 offset:0x1000
	ds_read_b64_tr_b16 v[232:233], v211 offset:0x1800
	ds_read_b64_tr_b16 v[234:235], v211 offset:0x2000
	ds_read_b64_tr_b16 v[236:237], v211 offset:0x2800
	ds_read_b64_tr_b16 v[238:239], v211 offset:0x3000
	ds_read_b64_tr_b16 v[240:241], v211 offset:0x3800
	s_waitcnt lgkmcnt(4)
	s_nop 0
	v_mfma_f32_32x32x16_bf16 v[18:33], v[138:141], v[226:229], v[18:33]
	ds_read_b64_tr_b16 v[226:227], v211 offset:0x200
	ds_read_b64_tr_b16 v[228:229], v211 offset:0xa00
	v_mfma_f32_32x32x16_bf16 v[18:33], v[222:225], v[230:233], v[18:33]
	ds_read_b64_tr_b16 v[230:231], v211 offset:0x1200
	ds_read_b64_tr_b16 v[232:233], v211 offset:0x1a00
	s_waitcnt lgkmcnt(4)
	v_mfma_f32_32x32x16_bf16 v[18:33], v[144:147], v[234:237], v[18:33]
	ds_read_b64_tr_b16 v[234:235], v211 offset:0x2200
	ds_read_b64_tr_b16 v[236:237], v211 offset:0x2a00
	v_mfma_f32_32x32x16_bf16 v[18:33], v[148:151], v[238:241], v[18:33]
	ds_read_b64_tr_b16 v[238:239], v211 offset:0x3200
	ds_read_b64_tr_b16 v[240:241], v211 offset:0x3a00
	s_waitcnt lgkmcnt(4)
	v_mfma_f32_32x32x16_bf16 v[2:17], v[138:141], v[226:229], v[2:17]
	ds_read_b64_tr_b16 v[226:227], v211 offset:0x400
	ds_read_b64_tr_b16 v[228:229], v211 offset:0xc00
	v_mfma_f32_32x32x16_bf16 v[2:17], v[222:225], v[230:233], v[2:17]
	ds_read_b64_tr_b16 v[230:231], v211 offset:0x1400
	ds_read_b64_tr_b16 v[232:233], v211 offset:0x1c00
	s_waitcnt lgkmcnt(4)
	v_mfma_f32_32x32x16_bf16 v[2:17], v[144:147], v[234:237], v[2:17]
	ds_read_b64_tr_b16 v[234:235], v211 offset:0x2400
	ds_read_b64_tr_b16 v[236:237], v211 offset:0x2c00
	v_mfma_f32_32x32x16_bf16 v[2:17], v[148:151], v[238:241], v[2:17]
	ds_read_b64_tr_b16 v[238:239], v211 offset:0x3400
	ds_read_b64_tr_b16 v[240:241], v211 offset:0x3c00
	s_waitcnt lgkmcnt(4)
	v_mfma_f32_32x32x16_bf16 v[50:65], v[138:141], v[226:229], v[50:65]
	ds_read_b64_tr_b16 v[226:227], v211 offset:0x600
	ds_read_b64_tr_b16 v[228:229], v211 offset:0xe00
	v_mfma_f32_32x32x16_bf16 v[50:65], v[222:225], v[230:233], v[50:65]
	ds_read_b64_tr_b16 v[230:231], v211 offset:0x1600
	ds_read_b64_tr_b16 v[232:233], v211 offset:0x1e00
	s_waitcnt lgkmcnt(4)
; #define SBAR() __builtin_amdgcn_sched_barrier(0)
; __device__ __forceinline__ void partialSM(f32x16& p0, f32x16& p1, float& m_reg, float& mn, float& alpha, float C, float thrRaw) {
;   float pmax = p0[0];
; #pragma unroll
;   for (int r = 1; r < 16; ++r) pmax = fmaxf(pmax, p0[r]);
; #pragma unroll
;   for (int r = 0; r < 16; ++r) pmax = fmaxf(pmax, p1[r]);
;   { auto rr = __builtin_amdgcn_permlane32_swap(__float_as_uint(pmax), __float_as_uint(pmax), false, false);
;     pmax = fmaxf(__uint_as_float(rr[0]), __uint_as_float(rr[1])); }
;   if (__builtin_expect(__all(pmax - m_reg <= thrRaw), 1)) { mn = m_reg; alpha = 1.f; }
;   else { mn = fmaxf(m_reg, pmax); alpha = __builtin_amdgcn_exp2f((m_reg - mn) * C); m_reg = mn; }
; template <int D0> __device__ __forceinline__ void pv_one(f32x16& od, int vb, bf16x8 pa0, bf16x8 pa1, bf16x8 pa2, bf16x8 pa3) {
;   const s16x4 l0 = tr_read<v_rd_off(D0, 0, 0)>(vb), h0 = tr_read<v_rd_off(D0, 0, 1)>(vb), l1 = tr_read<v_rd_off(D0, 1, 0)>(vb), h1 = tr_read<v_rd_off(D0, 1, 1)>(vb);
;   const s16x4 l2 = tr_read<v_rd_off(D0, 2, 0)>(vb), h2 = tr_read<v_rd_off(D0, 2, 1)>(vb), l3 = tr_read<v_rd_off(D0, 3, 0)>(vb), h3 = tr_read<v_rd_off(D0, 3, 1)>(vb);
;   asm volatile("s_waitcnt lgkmcnt(0)" ::: "memory"); SBAR();
;     ...
;   od = __builtin_amdgcn_mfma_f32_32x32x16_bf16(pa0, PK(l0, h0), od, 0, 0, 0);
;   od = __builtin_amdgcn_mfma_f32_32x32x16_bf16(pa1, PK(l1, h1), od, 0, 0, 0);
;   od = __builtin_amdgcn_mfma_f32_32x32x16_bf16(pa2, PK(l2, h2), od, 0, 0, 0);
;   od = __builtin_amdgcn_mfma_f32_32x32x16_bf16(pa3, PK(l3, h3), od, 0, 0, 0);
;     ...
; }
; __device__ __forceinline__ void pv_d0(f32x16* o, int vb, bf16x8 pa0, bf16x8 pa1, bf16x8 pa2, bf16x8 pa3) {
;   pv_one<0>(o[0], vb, pa0, pa1, pa2, pa3); pv_one<1>(o[1], vb, pa0, pa1, pa2, pa3); pv_one<2>(o[2], vb, pa0, pa1, pa2, pa3); pv_one<3>(o[3], vb, pa0, pa1, pa2, pa3);
	v_mfma_f32_32x32x16_bf16 v[50:65], v[144:147], v[234:237], v[50:65]
	ds_read_b64_tr_b16 v[234:235], v211 offset:0x2600
	ds_read_b64_tr_b16 v[236:237], v211 offset:0x2e00
	v_mfma_f32_32x32x16_bf16 v[50:65], v[148:151], v[238:241], v[50:65]
	ds_read_b64_tr_b16 v[238:239], v211 offset:0x3600
	ds_read_b64_tr_b16 v[240:241], v211 offset:0x3e00
	s_waitcnt lgkmcnt(6)
	v_mfma_f32_32x32x16_bf16 v[34:49], v[138:141], v[226:229], v[34:49]
	v_max_f32_e32 v138, v83, v82
	v_max3_f32 v138, v138, v84, v85
	v_max3_f32 v138, v138, v86, v87
	v_max3_f32 v138, v138, v88, v89
	v_max3_f32 v138, v138, v90, v91
	v_max3_f32 v138, v138, v92, v93
	v_max3_f32 v138, v138, v94, v95
	s_waitcnt lgkmcnt(4)
	v_mfma_f32_32x32x16_bf16 v[34:49], v[222:225], v[230:233], v[34:49]
	v_max3_f32 v138, v138, v96, v97
	v_max3_f32 v138, v138, v66, v67
	v_max3_f32 v138, v138, v68, v69
	v_max3_f32 v138, v138, v70, v71
	v_max3_f32 v138, v138, v72, v73
	v_max3_f32 v138, v138, v74, v75
	v_max3_f32 v138, v138, v76, v77
	v_max3_f32 v138, v138, v78, v79
	s_waitcnt lgkmcnt(2)
	v_mfma_f32_32x32x16_bf16 v[34:49], v[144:147], v[234:237], v[34:49]
	v_max3_f32 v138, v138, v80, v81
	v_mov_b32_e32 v139, v138
	s_nop 1
	v_permlane32_swap_b32_e32 v138, v139
	v_max_f32_e32 v138, v139, v138
	v_sub_f32_e32 v139, v138, v142
	s_mov_b32 s2, 0x42800000
	v_cmp_ge_f32_e32 vcc, s2, v139
	v_max_f32_e32 v138, v142, v138
	s_waitcnt lgkmcnt(0)
	v_mfma_f32_32x32x16_bf16 v[34:49], v[148:151], v[238:241], v[34:49]
	v_sub_f32_e32 v139, v142, v138
	v_mul_f32_e32 v139, 0x3e38aa3b, v139
	v_exp_f32_e32 v139, v139
	s_cmp_eq_u64 vcc, exec
	s_cselect_b64 s[2:3], -1, 0
	s_waitcnt vmcnt(3)
	v_cndmask_b32_e64 v222, v139, 1.0, s[2:3]
	v_cmp_gt_f32_e32 vcc, 1.0, v222
	ds_write_b128 v213, v[122:125] offset:32768
	s_cbranch_vccz .LBB0_686
	s_and_saveexec_b64 s[4:5], s[0:1]
	ds_write_b32 v208, v222 offset:128
	s_or_b64 exec, exec, s[4:5]
	s_waitcnt lgkmcnt(0)
	v_add_u32_e32 v139, v207, v0
	ds_read_b128 v[144:147], v139 offset:128
	ds_read_b128 v[148:151], v139 offset:160
	ds_read_b128 v[224:227], v139 offset:192
	ds_read_b128 v[228:231], v139 offset:224
	s_waitcnt lgkmcnt(3)
	v_pk_mul_f32 v[2:3], v[144:145], v[2:3]
	v_pk_mul_f32 v[4:5], v[4:5], v[146:147]
	s_waitcnt lgkmcnt(2)
	v_pk_mul_f32 v[6:7], v[6:7], v[148:149]
	v_pk_mul_f32 v[8:9], v[8:9], v[150:151]
	s_waitcnt lgkmcnt(1)
	v_pk_mul_f32 v[10:11], v[10:11], v[224:225]
	v_pk_mul_f32 v[12:13], v[12:13], v[226:227]
	s_waitcnt lgkmcnt(0)
	v_pk_mul_f32 v[14:15], v[14:15], v[228:229]
	v_pk_mul_f32 v[30:31], v[30:31], v[228:229]
	v_pk_mul_f32 v[26:27], v[26:27], v[224:225]
	v_pk_mul_f32 v[22:23], v[22:23], v[148:149]
	v_pk_mul_f32 v[32:33], v[32:33], v[230:231]
	v_pk_mul_f32 v[28:29], v[28:29], v[226:227]
	v_pk_mul_f32 v[24:25], v[24:25], v[150:151]
	v_pk_mul_f32 v[20:21], v[20:21], v[146:147]
	v_pk_mul_f32 v[18:19], v[18:19], v[144:145]
	v_pk_mul_f32 v[16:17], v[16:17], v[230:231]
	v_pk_mul_f32 v[34:35], v[144:145], v[34:35]
	v_pk_mul_f32 v[36:37], v[36:37], v[146:147]
	v_pk_mul_f32 v[38:39], v[38:39], v[148:149]
	v_pk_mul_f32 v[40:41], v[40:41], v[150:151]
	v_pk_mul_f32 v[42:43], v[42:43], v[224:225]
	v_pk_mul_f32 v[44:45], v[44:45], v[226:227]
	v_pk_mul_f32 v[46:47], v[46:47], v[228:229]
	v_pk_mul_f32 v[62:63], v[62:63], v[228:229]
	v_pk_mul_f32 v[58:59], v[58:59], v[224:225]
	v_pk_mul_f32 v[54:55], v[54:55], v[148:149]
	v_pk_mul_f32 v[64:65], v[64:65], v[230:231]
	v_pk_mul_f32 v[60:61], v[60:61], v[226:227]
	v_pk_mul_f32 v[56:57], v[56:57], v[150:151]
	v_pk_mul_f32 v[52:53], v[52:53], v[146:147]
	v_pk_mul_f32 v[50:51], v[50:51], v[144:145]
	v_pk_mul_f32 v[48:49], v[48:49], v[230:231]
; __device__ __forceinline__ void partialSM(f32x16& p0, f32x16& p1, float& m_reg, float& mn, float& alpha, float C, float thrRaw) {
;     ...
;   float mnC = -mn * C;
; #pragma unroll
;   for (int r = 0; r < 16; ++r) p0[r] = fmaf(p0[r], C, mnC);
; #pragma unroll
;   for (int r = 0; r < 16; ++r) p1[r] = fmaf(p1[r], C, mnC);
; #pragma unroll
;   for (int r = 0; r < 16; ++r) p0[r] = __builtin_amdgcn_exp2f(p0[r]);
; }
; __device__ __forceinline__ void finishSM(f32x16& p0, f32x16& p1, float alpha, float& l_reg, bf16x8& pa0, bf16x8& pa1, bf16x8& pa2, bf16x8& pa3) {
; #pragma unroll
;   for (int r = 0; r < 16; ++r) p1[r] = __builtin_amdgcn_exp2f(p1[r]);
;   float ps = 0;
; #pragma unroll
;   for (int r = 0; r < 16; ++r) ps += p0[r];
; #pragma unroll
;   for (int r = 0; r < 16; ++r) ps += p1[r];
;   { auto rr = __builtin_amdgcn_permlane32_swap(__float_as_uint(ps), __float_as_uint(ps), false, false);
;     ps = __uint_as_float(rr[0]) + __uint_as_float(rr[1]); }
;   l_reg = l_reg * alpha + ps;
;     ...
;   PK4(p0, 0, pa0); PK4(p0, 8, pa1); PK4(p1, 0, pa2); PK4(p1, 8, pa3);
;     ...
; }
; template <int DK, bool QL>
; __device__ __forceinline__ void qkt(f32x16& p0, f32x16& p1, const bf16* Ks, const bf16x8* qr, const char* ql, int r32, int hi) {
;   p0 = f32x16{}; p1 = f32x16{};
; #pragma unroll
;   for (int d0 = 0; d0 < DK / 16; ++d0) { int cb = (d0 * 16 + hi * 8) * 2;
;     const bf16x8 qv = QL ? *reinterpret_cast<const bf16x8*>(ql + d0 * 1024) : qr[d0];
;     bf16x8 b0 = *reinterpret_cast<const bf16x8*>((const char*)Ks + kswz<DK>(r32, cb));
;     bf16x8 b1 = *reinterpret_cast<const bf16x8*>((const char*)Ks + kswz<DK>(32 + r32, cb));
;     p0 = __builtin_amdgcn_mfma_f32_32x32x16_bf16(b0, qv, p0, 0, 0, 0);
;     p1 = __builtin_amdgcn_mfma_f32_32x32x16_bf16(b1, qv, p1, 0, 0, 0); }
; }
.LBB0_686:
	v_cndmask_b32_e64 v223, v138, v142, s[2:3]
	v_mul_f32_e32 v224, 0xbe38aa3b, v223
	s_mov_b32 s2, 0x3e38aa3b
	v_pk_fma_f32 v[82:83], v[82:83], s[2:3], v[224:225] op_sel_hi:[1,0,0]
	v_pk_fma_f32 v[84:85], v[84:85], s[2:3], v[224:225] op_sel_hi:[1,0,0]
	v_pk_fma_f32 v[86:87], v[86:87], s[2:3], v[224:225] op_sel_hi:[1,0,0]
	v_pk_fma_f32 v[88:89], v[88:89], s[2:3], v[224:225] op_sel_hi:[1,0,0]
	v_pk_fma_f32 v[90:91], v[90:91], s[2:3], v[224:225] op_sel_hi:[1,0,0]
	v_pk_fma_f32 v[92:93], v[92:93], s[2:3], v[224:225] op_sel_hi:[1,0,0]
	v_pk_fma_f32 v[94:95], v[94:95], s[2:3], v[224:225] op_sel_hi:[1,0,0]
	v_pk_fma_f32 v[96:97], v[96:97], s[2:3], v[224:225] op_sel_hi:[1,0,0]
	v_exp_f32_e32 v138, v82
	v_exp_f32_e32 v153, v83
	v_exp_f32_e32 v139, v84
	v_exp_f32_e32 v152, v85
	v_exp_f32_e32 v140, v86
	v_exp_f32_e32 v151, v87
	v_exp_f32_e32 v141, v88
	v_exp_f32_e32 v150, v89
	v_exp_f32_e32 v142, v90
	v_exp_f32_e32 v149, v91
	v_exp_f32_e32 v143, v92
	v_exp_f32_e32 v148, v93
	v_exp_f32_e32 v144, v94
	v_exp_f32_e32 v147, v95
	v_exp_f32_e32 v145, v96
	v_exp_f32_e32 v146, v97
	v_fmamk_f32 v233, v66, 0x3e38aa3b, v224
	v_fmamk_f32 v234, v67, 0x3e38aa3b, v224
	v_fmamk_f32 v235, v68, 0x3e38aa3b, v224
	v_fmamk_f32 v236, v69, 0x3e38aa3b, v224
	v_fmamk_f32 v237, v70, 0x3e38aa3b, v224
	v_fmamk_f32 v226, v71, 0x3e38aa3b, v224
	v_fmamk_f32 v227, v72, 0x3e38aa3b, v224
	v_fmamk_f32 v228, v73, 0x3e38aa3b, v224
	v_fmamk_f32 v229, v74, 0x3e38aa3b, v224
	v_fmamk_f32 v230, v75, 0x3e38aa3b, v224
	v_fmamk_f32 v231, v76, 0x3e38aa3b, v224
	v_fmamk_f32 v232, v77, 0x3e38aa3b, v224
	v_fmamk_f32 v225, v78, 0x3e38aa3b, v224
	v_fmamk_f32 v238, v79, 0x3e38aa3b, v224
	v_fmamk_f32 v239, v80, 0x3e38aa3b, v224
	v_fmac_f32_e32 v224, 0x3e38aa3b, v81
	s_waitcnt lgkmcnt(0)
	s_barrier
	ds_write_b128 v214, v[114:117]
	ds_write_b128 v215, v[118:121]
	ds_read_b128 v[66:69], v212 offset:32768
	ds_read_b128 v[70:73], v212 offset:36864
	v_exp_f32_e32 v164, v233
	v_exp_f32_e32 v233, v224
	v_add_f32_e32 v224, v153, v138
	s_waitcnt lgkmcnt(1)
	v_mfma_f32_32x32x16_bf16 v[82:97], v[66:69], v[110:113], 0
	v_add_f32_e32 v224, v139, v224
	v_add_f32_e32 v224, v152, v224
	v_add_f32_e32 v224, v140, v224
	ds_read_b128 v[240:243], v216 offset:32768
	ds_read_b128 v[244:247], v216 offset:36864
	v_add_f32_e32 v224, v151, v224
	v_add_f32_e32 v224, v141, v224
	v_add_f32_e32 v224, v150, v224
	s_waitcnt lgkmcnt(2)
	v_mfma_f32_32x32x16_bf16 v[66:81], v[70:73], v[110:113], 0
	v_add_f32_e32 v224, v142, v224
	v_add_f32_e32 v224, v149, v224
	v_add_f32_e32 v224, v143, v224
	v_add_f32_e32 v224, v148, v224
	v_add_f32_e32 v224, v144, v224
	v_exp_f32_e32 v165, v234
	v_add_f32_e32 v224, v147, v224
	s_waitcnt lgkmcnt(1)
	v_mfma_f32_32x32x16_bf16 v[82:97], v[240:243], v[106:109], v[82:97]
	v_exp_f32_e32 v166, v235
	v_add_f32_e32 v224, v145, v224
	v_exp_f32_e32 v167, v236
	v_add_f32_e32 v224, v146, v224
	v_exp_f32_e32 v172, v237
	v_add_f32_e32 v224, v164, v224
	v_exp_f32_e32 v173, v226
	s_waitcnt lgkmcnt(0)
	v_mfma_f32_32x32x16_bf16 v[66:81], v[244:247], v[106:109], v[66:81]
	ds_read_b128 v[240:243], v217 offset:32768
	ds_read_b128 v[244:247], v217 offset:36864
	v_add_f32_e32 v224, v165, v224
	v_exp_f32_e32 v174, v227
	v_add_f32_e32 v224, v166, v224
	v_exp_f32_e32 v175, v228
	v_add_f32_e32 v224, v167, v224
	v_exp_f32_e32 v226, v229
	s_waitcnt lgkmcnt(1)
	v_mfma_f32_32x32x16_bf16 v[82:97], v[240:243], v[98:101], v[82:97]
	v_add_f32_e32 v224, v172, v224
	v_exp_f32_e32 v227, v230
	v_add_f32_e32 v224, v173, v224
	v_exp_f32_e32 v228, v231
	v_add_f32_e32 v224, v174, v224
	v_exp_f32_e32 v229, v232
	v_add_f32_e32 v224, v175, v224
	s_waitcnt lgkmcnt(0)
	v_mfma_f32_32x32x16_bf16 v[66:81], v[244:247], v[98:101], v[66:81]
	ds_read_b128 v[240:243], v218 offset:32768
	ds_read_b128 v[244:247], v218 offset:36864
	v_exp_f32_e32 v230, v225
	v_add_f32_e32 v224, v226, v224
	v_exp_f32_e32 v231, v238
	v_add_f32_e32 v224, v227, v224
	v_exp_f32_e32 v232, v239
	v_add_f32_e32 v224, v228, v224
	s_waitcnt lgkmcnt(1)
	v_mfma_f32_32x32x16_bf16 v[82:97], v[240:243], v[102:105], v[82:97]
	v_add_f32_e32 v224, v229, v224
	v_add_f32_e32 v224, v230, v224
	v_add_f32_e32 v224, v231, v224
	v_add_f32_e32 v224, v232, v224
	v_add_f32_e32 v224, v233, v224
	v_cvt_pk_bf16_f32 v138, v138, v153
	s_waitcnt lgkmcnt(0)
	v_mfma_f32_32x32x16_bf16 v[66:81], v[244:247], v[102:105], v[66:81]
	v_cvt_pk_bf16_f32 v139, v139, v152
	v_cvt_pk_bf16_f32 v140, v140, v151
	v_cvt_pk_bf16_f32 v141, v141, v150
	v_cvt_pk_bf16_f32 v142, v142, v149
	v_cvt_pk_bf16_f32 v143, v143, v148
	v_cvt_pk_bf16_f32 v144, v144, v147
	v_cvt_pk_bf16_f32 v145, v145, v146
	v_cvt_pk_bf16_f32 v146, v164, v165
	v_cvt_pk_bf16_f32 v147, v166, v167
	v_cvt_pk_bf16_f32 v148, v172, v173
	v_cvt_pk_bf16_f32 v149, v174, v175
	v_cvt_pk_bf16_f32 v150, v226, v227
	v_cvt_pk_bf16_f32 v151, v228, v229
	v_cvt_pk_bf16_f32 v152, v230, v231
	v_cvt_pk_bf16_f32 v153, v232, v233
	s_cmp_gt_u32 s9, 60
	s_cselect_b64 s[4:5], -1, 0
	s_and_b64 vcc, exec, s[4:5]
	s_cbranch_vccnz .Lod_d1
	global_load_dwordx4 v[114:117], v[178:179], off offset:2048
	global_load_dwordx4 v[118:121], v[180:181], off offset:2048
	global_load_dwordx4 v[122:125], v[204:205], off offset:1024
	s_mov_b32 s6, 0xa0000
	s_mov_b32 s7, 0
	s_nop 0
	v_lshl_add_u64 v[178:179], v[178:179], 0, s[6:7]
	v_lshl_add_u64 v[180:181], v[180:181], 0, s[6:7]
	v_lshl_add_u64 v[204:205], v[204:205], 0, s[6:7]

; __device__ __forceinline__ void partialSM(f32x16& p0, f32x16& p1, float& m_reg, float& mn, float& alpha, float C, float thrRaw) {
;     ...
;   float mnC = -mn * C;
; #pragma unroll
;   for (int r = 0; r < 16; ++r) p0[r] = fmaf(p0[r], C, mnC);
; #pragma unroll
;   for (int r = 0; r < 16; ++r) p1[r] = fmaf(p1[r], C, mnC);
; #pragma unroll
;   for (int r = 0; r < 16; ++r) p0[r] = __builtin_amdgcn_exp2f(p0[r]);
; }
; __device__ __forceinline__ void finishSM(f32x16& p0, f32x16& p1, float alpha, float& l_reg, bf16x8& pa0, bf16x8& pa1, bf16x8& pa2, bf16x8& pa3) {
; #pragma unroll
;   for (int r = 0; r < 16; ++r) p1[r] = __builtin_amdgcn_exp2f(p1[r]);
;   float ps = 0;
; #pragma unroll
;   for (int r = 0; r < 16; ++r) ps += p0[r];
; #pragma unroll
;   for (int r = 0; r < 16; ++r) ps += p1[r];
;   { auto rr = __builtin_amdgcn_permlane32_swap(__float_as_uint(ps), __float_as_uint(ps), false, false);
;     ps = __uint_as_float(rr[0]) + __uint_as_float(rr[1]); }
;   l_reg = l_reg * alpha + ps;
.LBB0_692:
	v_cndmask_b32_e64 v142, v138, v223, s[2:3]
	v_mul_f32_e32 v132, 0xbe38aa3b, v142
	v_mov_b32_e32 v133, v132
	s_mov_b32 s2, 0x3e38aa3b
	v_pk_fma_f32 v[82:83], v[82:83], s[2:3], v[132:133] op_sel_hi:[1,0,0]
	v_pk_fma_f32 v[84:85], v[84:85], s[2:3], v[132:133] op_sel_hi:[1,0,0]
	v_pk_fma_f32 v[86:87], v[86:87], s[2:3], v[132:133] op_sel_hi:[1,0,0]
	v_pk_fma_f32 v[88:89], v[88:89], s[2:3], v[132:133] op_sel_hi:[1,0,0]
	v_pk_fma_f32 v[90:91], v[90:91], s[2:3], v[132:133] op_sel_hi:[1,0,0]
	v_pk_fma_f32 v[92:93], v[92:93], s[2:3], v[132:133] op_sel_hi:[1,0,0]
	v_pk_fma_f32 v[94:95], v[94:95], s[2:3], v[132:133] op_sel_hi:[1,0,0]
	v_fmamk_f32 v96, v96, 0x3e38aa3b, v132
	v_fmac_f32_e32 v133, 0x3e38aa3b, v97
	s_mov_b32 s2, 0x3e38aa3b
	v_exp_f32_e32 v177, v82
	v_exp_f32_e32 v226, v83
	v_exp_f32_e32 v161, v84
	v_exp_f32_e32 v223, v85
	v_exp_f32_e32 v153, v86
	v_exp_f32_e32 v176, v87
	v_exp_f32_e32 v152, v88
	v_exp_f32_e32 v160, v89
	v_exp_f32_e32 v149, v90
	v_exp_f32_e32 v151, v91
	v_exp_f32_e32 v147, v92
	v_exp_f32_e32 v150, v93
	v_exp_f32_e32 v145, v94
	v_exp_f32_e32 v148, v95
	v_exp_f32_e32 v144, v96
	v_exp_f32_e32 v146, v133
	v_pk_fma_f32 v[138:139], v[66:67], s[2:3], v[132:133] op_sel_hi:[1,0,0]
	v_pk_fma_f32 v[136:137], v[68:69], s[2:3], v[132:133] op_sel_hi:[1,0,0]
	v_pk_fma_f32 v[130:131], v[70:71], s[2:3], v[132:133] op_sel_hi:[1,0,0]
	v_pk_fma_f32 v[128:129], v[72:73], s[2:3], v[132:133] op_sel_hi:[1,0,0]
	v_pk_fma_f32 v[126:127], v[74:75], s[2:3], v[132:133] op_sel_hi:[1,0,0]
	v_pk_fma_f32 v[140:141], v[76:77], s[2:3], v[132:133] op_sel_hi:[1,0,0]
	v_pk_fma_f32 v[134:135], v[78:79], s[2:3], v[132:133] op_sel_hi:[1,0,0]
	v_pk_fma_f32 v[132:133], v[80:81], s[2:3], v[132:133] op_sel_hi:[1,0,0]
	v_fma_f32 v66, v219, v209, v220
	v_fma_f32 v209, v66, v222, v224
	s_add_i32 s9, s9, 2
	s_and_b64 vcc, exec, s[4:5]
	s_waitcnt lgkmcnt(0)
	s_barrier
	s_cbranch_vccnz .LBB0_694
	v_mov_b32_e32 v219, v143
	ds_write_b128 v214, v[182:185] offset:16384
	ds_write_b128 v215, v[194:197] offset:16384
	s_branch .LBB0_682

; #define SBAR() __builtin_amdgcn_sched_barrier(0)
; #define HOOK(P0, P1, j) do { if (NA) na_hook(P0, P1, krow0 + (j), q_row, q_col, win_r, win_c, rpb, inv_scale, hi); } while (0)
; __device__ __forceinline__ void finishSM(f32x16& p0, f32x16& p1, float alpha, float& l_reg, bf16x8& pa0, bf16x8& pa1, bf16x8& pa2, bf16x8& pa3) {
; #pragma unroll
;   for (int r = 0; r < 16; ++r) p1[r] = __builtin_amdgcn_exp2f(p1[r]);
;   float ps = 0;
; #pragma unroll
;   for (int r = 0; r < 16; ++r) ps += p0[r];
; #pragma unroll
;   for (int r = 0; r < 16; ++r) ps += p1[r];
;   { auto rr = __builtin_amdgcn_permlane32_swap(__float_as_uint(ps), __float_as_uint(ps), false, false);
;     ps = __uint_as_float(rr[0]) + __uint_as_float(rr[1]); }
;   l_reg = l_reg * alpha + ps;
;     ...
;   PK4(p0, 0, pa0); PK4(p0, 8, pa1); PK4(p1, 0, pa2); PK4(p1, 8, pa3);
;     ...
; }
; template <int DK, bool QL>
; __device__ __forceinline__ void qkt(f32x16& p0, f32x16& p1, const bf16* Ks, const bf16x8* qr, const char* ql, int r32, int hi) {
;   p0 = f32x16{}; p1 = f32x16{};
; #pragma unroll
;   for (int d0 = 0; d0 < DK / 16; ++d0) { int cb = (d0 * 16 + hi * 8) * 2;
;     const bf16x8 qv = QL ? *reinterpret_cast<const bf16x8*>(ql + d0 * 1024) : qr[d0];
;     bf16x8 b0 = *reinterpret_cast<const bf16x8*>((const char*)Ks + kswz<DK>(r32, cb));
;     bf16x8 b1 = *reinterpret_cast<const bf16x8*>((const char*)Ks + kswz<DK>(32 + r32, cb));
;     p0 = __builtin_amdgcn_mfma_f32_32x32x16_bf16(b0, qv, p0, 0, 0, 0);
;     p1 = __builtin_amdgcn_mfma_f32_32x32x16_bf16(b1, qv, p1, 0, 0, 0); }
; }
; template <int DK, bool NA, bool QL, int SD> ...
;     ...
;   SBAR(); qkt<DK, QL>(pB0, pB1, (bf16*)((char*)K_lds + SHM_K), qr, ql, r32, hi); HOOK(pB0, pB1, NT - 1);
;   finishSM(pA0, pA1, alA, l_reg, pa0, pa1, pa2, pa3); SBAR();
;   pv_d0(o, vb0, pa0, pa1, pa2, pa3); partialSM(pB0, pB1, m_reg, mnB, alB, C, thrRaw);
.LBB0_694:
	v_mov_b32_e32 v221, v209
	s_nop 1
	v_permlane32_swap_b32_e32 v209, v221
	v_add_f32_e32 v209, v209, v221
	ds_write_b128 v214, v[182:185] offset:16384
	ds_write_b128 v215, v[194:197] offset:16384
	ds_read_b128 v[66:69], v212 offset:49152
	ds_read_b128 v[70:73], v212 offset:53248
	v_exp_f32_e32 v118, v140
	v_exp_f32_e32 v119, v141
	v_exp_f32_e32 v120, v134
	s_waitcnt lgkmcnt(1)
	v_mfma_f32_32x32x16_bf16 v[82:97], v[66:69], v[110:113], 0
	v_exp_f32_e32 v121, v135
	v_exp_f32_e32 v122, v132
	v_exp_f32_e32 v123, v133
	s_waitcnt lgkmcnt(0)
	v_mfma_f32_32x32x16_bf16 v[66:81], v[70:73], v[110:113], 0
	ds_read_b128 v[110:113], v216 offset:49152
	ds_read_b128 v[114:117], v216 offset:53248
	s_waitcnt lgkmcnt(1)
	v_mfma_f32_32x32x16_bf16 v[82:97], v[110:113], v[106:109], v[82:97]
	s_waitcnt lgkmcnt(0)
	v_mfma_f32_32x32x16_bf16 v[66:81], v[114:117], v[106:109], v[66:81]
	ds_read_b128 v[106:109], v217 offset:49152
	ds_read_b128 v[110:113], v217 offset:53248
	v_exp_f32_e32 v114, v128
	v_exp_f32_e32 v115, v129
	v_exp_f32_e32 v116, v126
	v_exp_f32_e32 v117, v127
	s_waitcnt lgkmcnt(1)
	v_mfma_f32_32x32x16_bf16 v[82:97], v[106:109], v[98:101], v[82:97]
	s_waitcnt lgkmcnt(0)
	v_mfma_f32_32x32x16_bf16 v[66:81], v[110:113], v[98:101], v[66:81]
	ds_read_b128 v[98:101], v218 offset:49152
	ds_read_b128 v[106:109], v218 offset:53248
	v_exp_f32_e32 v110, v136
	v_exp_f32_e32 v111, v137
	v_exp_f32_e32 v112, v130
	v_exp_f32_e32 v113, v131
	s_waitcnt lgkmcnt(1)
	v_mfma_f32_32x32x16_bf16 v[82:97], v[98:101], v[102:105], v[82:97]
	v_add_f32_e32 v98, 0, v177
	v_add_f32_e32 v98, v226, v98
	v_add_f32_e32 v98, v161, v98
	v_add_f32_e32 v98, v223, v98
	v_add_f32_e32 v98, v153, v98
	v_add_f32_e32 v98, v176, v98
	v_add_f32_e32 v98, v152, v98
	v_add_f32_e32 v98, v160, v98
	v_add_f32_e32 v98, v149, v98
	v_add_f32_e32 v98, v151, v98
	v_add_f32_e32 v98, v147, v98
	v_add_f32_e32 v98, v150, v98
	s_waitcnt lgkmcnt(0)
	v_mfma_f32_32x32x16_bf16 v[66:81], v[106:109], v[102:105], v[66:81]
	v_exp_f32_e32 v108, v138
	v_add_f32_e32 v98, v145, v98
	v_exp_f32_e32 v109, v139
	v_add_f32_e32 v98, v148, v98
	v_add_f32_e32 v98, v144, v98
	v_add_f32_e32 v98, v146, v98
	v_add_f32_e32 v98, v108, v98
	v_add_f32_e32 v98, v109, v98
	v_add_f32_e32 v98, v110, v98
	v_add_f32_e32 v98, v111, v98
	v_add_f32_e32 v98, v112, v98
	v_add_f32_e32 v98, v113, v98
	v_add_f32_e32 v98, v114, v98
	v_add_f32_e32 v98, v115, v98
	v_add_f32_e32 v98, v116, v98
	v_add_f32_e32 v98, v117, v98
	v_add_f32_e32 v98, v118, v98
	v_add_f32_e32 v98, v119, v98
	v_add_f32_e32 v98, v120, v98
	v_add_f32_e32 v98, v121, v98
	v_add_f32_e32 v98, v122, v98
	v_add_f32_e32 v98, v123, v98
	v_mov_b32_e32 v99, v98
	v_cvt_pk_bf16_f32 v100, v177, v226
	v_cvt_pk_bf16_f32 v101, v161, v223
	v_cvt_pk_bf16_f32 v102, v153, v176
	v_cvt_pk_bf16_f32 v103, v152, v160
	s_nop 1
	v_permlane32_swap_b32_e32 v98, v99
	v_cvt_pk_bf16_f32 v104, v149, v151
	v_cvt_pk_bf16_f32 v105, v147, v150
	v_cvt_pk_bf16_f32 v106, v145, v148
	v_cvt_pk_bf16_f32 v107, v144, v146
	v_cvt_pk_bf16_f32 v108, v108, v109
	v_cvt_pk_bf16_f32 v109, v110, v111
	v_cvt_pk_bf16_f32 v110, v112, v113
	v_cvt_pk_bf16_f32 v111, v114, v115
	v_cvt_pk_bf16_f32 v112, v116, v117
	v_cvt_pk_bf16_f32 v113, v118, v119
	v_cvt_pk_bf16_f32 v114, v120, v121
	v_cvt_pk_bf16_f32 v115, v122, v123
	s_nop 0
	ds_read_b64_tr_b16 v[116:117], v211 offset:0
	ds_read_b64_tr_b16 v[118:119], v211 offset:0x800
	ds_read_b64_tr_b16 v[120:121], v211 offset:0x1000
	ds_read_b64_tr_b16 v[122:123], v211 offset:0x1800
	ds_read_b64_tr_b16 v[124:125], v211 offset:0x2000
	ds_read_b64_tr_b16 v[126:127], v211 offset:0x2800
	ds_read_b64_tr_b16 v[128:129], v211 offset:0x3000
	ds_read_b64_tr_b16 v[130:131], v211 offset:0x3800
	s_waitcnt lgkmcnt(0)
	s_nop 0
	v_mfma_f32_32x32x16_bf16 v[18:33], v[100:103], v[116:119], v[18:33]
	ds_read_b64_tr_b16 v[116:117], v211 offset:0x200
	ds_read_b64_tr_b16 v[118:119], v211 offset:0xa00
	v_mfma_f32_32x32x16_bf16 v[18:33], v[104:107], v[120:123], v[18:33]
	ds_read_b64_tr_b16 v[120:121], v211 offset:0x1200
	ds_read_b64_tr_b16 v[122:123], v211 offset:0x1a00
	v_mfma_f32_32x32x16_bf16 v[18:33], v[108:111], v[124:127], v[18:33]
	ds_read_b64_tr_b16 v[124:125], v211 offset:0x2200
	ds_read_b64_tr_b16 v[126:127], v211 offset:0x2a00
	v_mfma_f32_32x32x16_bf16 v[18:33], v[112:115], v[128:131], v[18:33]
	ds_read_b64_tr_b16 v[128:129], v211 offset:0x3200
	ds_read_b64_tr_b16 v[130:131], v211 offset:0x3a00
	s_waitcnt lgkmcnt(0)
; #define SBAR() __builtin_amdgcn_sched_barrier(0)
; __device__ __forceinline__ void partialSM(f32x16& p0, f32x16& p1, float& m_reg, float& mn, float& alpha, float C, float thrRaw) {
;   float pmax = p0[0];
; #pragma unroll
;   for (int r = 1; r < 16; ++r) pmax = fmaxf(pmax, p0[r]);
; #pragma unroll
;   for (int r = 0; r < 16; ++r) pmax = fmaxf(pmax, p1[r]);
;   { auto rr = __builtin_amdgcn_permlane32_swap(__float_as_uint(pmax), __float_as_uint(pmax), false, false);
;     pmax = fmaxf(__uint_as_float(rr[0]), __uint_as_float(rr[1])); }
;   if (__builtin_expect(__all(pmax - m_reg <= thrRaw), 1)) { mn = m_reg; alpha = 1.f; }
;   else { mn = fmaxf(m_reg, pmax); alpha = __builtin_amdgcn_exp2f((m_reg - mn) * C); m_reg = mn; }
; template <int D0> __device__ __forceinline__ void pv_one(f32x16& od, int vb, bf16x8 pa0, bf16x8 pa1, bf16x8 pa2, bf16x8 pa3) {
;   const s16x4 l0 = tr_read<v_rd_off(D0, 0, 0)>(vb), h0 = tr_read<v_rd_off(D0, 0, 1)>(vb), l1 = tr_read<v_rd_off(D0, 1, 0)>(vb), h1 = tr_read<v_rd_off(D0, 1, 1)>(vb);
;   const s16x4 l2 = tr_read<v_rd_off(D0, 2, 0)>(vb), h2 = tr_read<v_rd_off(D0, 2, 1)>(vb), l3 = tr_read<v_rd_off(D0, 3, 0)>(vb), h3 = tr_read<v_rd_off(D0, 3, 1)>(vb);
;   asm volatile("s_waitcnt lgkmcnt(0)" ::: "memory"); SBAR();
;     ...
;   od = __builtin_amdgcn_mfma_f32_32x32x16_bf16(pa0, PK(l0, h0), od, 0, 0, 0);
;   od = __builtin_amdgcn_mfma_f32_32x32x16_bf16(pa1, PK(l1, h1), od, 0, 0, 0);
;   od = __builtin_amdgcn_mfma_f32_32x32x16_bf16(pa2, PK(l2, h2), od, 0, 0, 0);
;   od = __builtin_amdgcn_mfma_f32_32x32x16_bf16(pa3, PK(l3, h3), od, 0, 0, 0);
;     ...
; }
; __device__ __forceinline__ void pv_d0(f32x16* o, int vb, bf16x8 pa0, bf16x8 pa1, bf16x8 pa2, bf16x8 pa3) {
;   pv_one<0>(o[0], vb, pa0, pa1, pa2, pa3); pv_one<1>(o[1], vb, pa0, pa1, pa2, pa3); pv_one<2>(o[2], vb, pa0, pa1, pa2, pa3); pv_one<3>(o[3], vb, pa0, pa1, pa2, pa3);
	v_mfma_f32_32x32x16_bf16 v[2:17], v[100:103], v[116:119], v[2:17]
	ds_read_b64_tr_b16 v[116:117], v211 offset:0x400
	ds_read_b64_tr_b16 v[118:119], v211 offset:0xc00
	v_mfma_f32_32x32x16_bf16 v[2:17], v[104:107], v[120:123], v[2:17]
	ds_read_b64_tr_b16 v[120:121], v211 offset:0x1400
	ds_read_b64_tr_b16 v[122:123], v211 offset:0x1c00
	v_mfma_f32_32x32x16_bf16 v[2:17], v[108:111], v[124:127], v[2:17]
	ds_read_b64_tr_b16 v[124:125], v211 offset:0x2400
	ds_read_b64_tr_b16 v[126:127], v211 offset:0x2c00
	v_mfma_f32_32x32x16_bf16 v[2:17], v[112:115], v[128:131], v[2:17]
	ds_read_b64_tr_b16 v[128:129], v211 offset:0x3400
	ds_read_b64_tr_b16 v[130:131], v211 offset:0x3c00
	s_waitcnt lgkmcnt(0)
	v_mfma_f32_32x32x16_bf16 v[50:65], v[100:103], v[116:119], v[50:65]
	ds_read_b64_tr_b16 v[116:117], v211 offset:0x600
	ds_read_b64_tr_b16 v[118:119], v211 offset:0xe00
	v_mfma_f32_32x32x16_bf16 v[50:65], v[104:107], v[120:123], v[50:65]
	ds_read_b64_tr_b16 v[120:121], v211 offset:0x1600
	ds_read_b64_tr_b16 v[122:123], v211 offset:0x1e00
	v_mfma_f32_32x32x16_bf16 v[50:65], v[108:111], v[124:127], v[50:65]
	ds_read_b64_tr_b16 v[124:125], v211 offset:0x2600
	ds_read_b64_tr_b16 v[126:127], v211 offset:0x2e00
	v_mfma_f32_32x32x16_bf16 v[50:65], v[112:115], v[128:131], v[50:65]
	ds_read_b64_tr_b16 v[128:129], v211 offset:0x3600
	ds_read_b64_tr_b16 v[130:131], v211 offset:0x3e00
	s_waitcnt lgkmcnt(0)
	v_mfma_f32_32x32x16_bf16 v[34:49], v[100:103], v[116:119], v[34:49]
	v_max_f32_e32 v100, v83, v83
	v_max_f32_e32 v101, v82, v82
	v_max_f32_e32 v100, v101, v100
	v_max3_f32 v100, v100, v84, v85
	v_max3_f32 v100, v100, v86, v87
	v_max3_f32 v100, v100, v88, v89
	v_max3_f32 v100, v100, v90, v91
	v_max3_f32 v100, v100, v92, v93
	v_max3_f32 v100, v100, v94, v95
	v_mfma_f32_32x32x16_bf16 v[34:49], v[104:107], v[120:123], v[34:49]
	v_max3_f32 v100, v100, v96, v97
	v_max3_f32 v100, v100, v66, v67
	v_max3_f32 v100, v100, v68, v69
	v_max3_f32 v100, v100, v70, v71
	v_max3_f32 v100, v100, v72, v73
	v_max3_f32 v100, v100, v74, v75
	v_max3_f32 v100, v100, v76, v77
	v_max3_f32 v100, v100, v78, v79
	v_mfma_f32_32x32x16_bf16 v[34:49], v[108:111], v[124:127], v[34:49]
	v_max3_f32 v100, v100, v80, v81
	v_mov_b32_e32 v101, v100
	s_nop 1
	v_permlane32_swap_b32_e32 v100, v101
	v_max_f32_e32 v101, v101, v101
	v_max_f32_e32 v100, v100, v100
	v_max_f32_e32 v100, v100, v101
	v_sub_f32_e32 v101, v100, v142
	s_mov_b32 s2, 0x42800000
	v_cmp_ge_f32_e32 vcc, s2, v101
	v_max_f32_e32 v101, v142, v142
	v_max_f32_e32 v101, v101, v100
	v_mfma_f32_32x32x16_bf16 v[34:49], v[112:115], v[128:131], v[34:49]
	v_sub_f32_e32 v100, v142, v101
	v_mul_f32_e32 v100, 0x3e38aa3b, v100
	v_exp_f32_e32 v100, v100
	s_cmp_eq_u64 vcc, exec
	s_cselect_b64 s[2:3], -1, 0
	v_cndmask_b32_e64 v100, v100, 1.0, s[2:3]
	v_cmp_gt_f32_e32 vcc, 1.0, v100
	s_barrier
	s_cbranch_vccz .LBB0_698
	s_and_saveexec_b64 s[4:5], s[0:1]
	ds_write_b32 v208, v100 offset:128
	s_or_b64 exec, exec, s[4:5]
	s_waitcnt lgkmcnt(0)
	v_add_u32_e32 v114, v207, v0
	ds_read_b128 v[102:105], v114 offset:224
	ds_read_b128 v[106:109], v114 offset:192
	ds_read_b128 v[110:113], v114 offset:160
	ds_read_b128 v[114:117], v114 offset:128
	s_waitcnt lgkmcnt(3)
	v_pk_mul_f32 v[30:31], v[30:31], v[102:103]
	s_waitcnt lgkmcnt(2)
	v_pk_mul_f32 v[26:27], v[26:27], v[106:107]
	s_waitcnt lgkmcnt(1)
	v_pk_mul_f32 v[22:23], v[22:23], v[110:111]
	v_pk_mul_f32 v[32:33], v[32:33], v[104:105]
	v_pk_mul_f32 v[28:29], v[28:29], v[108:109]
	v_pk_mul_f32 v[24:25], v[24:25], v[112:113]
	s_waitcnt lgkmcnt(0)
	v_pk_mul_f32 v[20:21], v[20:21], v[116:117]
	v_pk_mul_f32 v[18:19], v[18:19], v[114:115]
	v_pk_mul_f32 v[14:15], v[102:103], v[14:15]
	v_pk_mul_f32 v[10:11], v[106:107], v[10:11]
	v_pk_mul_f32 v[6:7], v[110:111], v[6:7]
	v_pk_mul_f32 v[16:17], v[104:105], v[16:17]
	v_pk_mul_f32 v[12:13], v[108:109], v[12:13]
	v_pk_mul_f32 v[8:9], v[112:113], v[8:9]
	v_pk_mul_f32 v[4:5], v[116:117], v[4:5]
	v_pk_mul_f32 v[2:3], v[114:115], v[2:3]
	v_pk_mul_f32 v[62:63], v[102:103], v[62:63]
	v_pk_mul_f32 v[58:59], v[106:107], v[58:59]
	v_pk_mul_f32 v[54:55], v[110:111], v[54:55]
	v_pk_mul_f32 v[64:65], v[104:105], v[64:65]
	v_pk_mul_f32 v[60:61], v[108:109], v[60:61]
	v_pk_mul_f32 v[56:57], v[112:113], v[56:57]
	v_pk_mul_f32 v[52:53], v[116:117], v[52:53]
	v_pk_mul_f32 v[50:51], v[114:115], v[50:51]
	v_pk_mul_f32 v[46:47], v[102:103], v[46:47]
	v_pk_mul_f32 v[42:43], v[106:107], v[42:43]
	v_pk_mul_f32 v[38:39], v[110:111], v[38:39]
	v_pk_mul_f32 v[48:49], v[104:105], v[48:49]
	v_pk_mul_f32 v[44:45], v[108:109], v[44:45]
	v_pk_mul_f32 v[40:41], v[112:113], v[40:41]
	v_pk_mul_f32 v[36:37], v[116:117], v[36:37]
	v_pk_mul_f32 v[34:35], v[114:115], v[34:35]

; #define SBAR() __builtin_amdgcn_sched_barrier(0)
; __device__ __forceinline__ void finishSM(f32x16& p0, f32x16& p1, float alpha, float& l_reg, bf16x8& pa0, bf16x8& pa1, bf16x8& pa2, bf16x8& pa3) {
; #pragma unroll
;   for (int r = 0; r < 16; ++r) p1[r] = __builtin_amdgcn_exp2f(p1[r]);
;   float ps = 0;
; #pragma unroll
;   for (int r = 0; r < 16; ++r) ps += p0[r];
; #pragma unroll
;   for (int r = 0; r < 16; ++r) ps += p1[r];
;   { auto rr = __builtin_amdgcn_permlane32_swap(__float_as_uint(ps), __float_as_uint(ps), false, false);
;     ps = __uint_as_float(rr[0]) + __uint_as_float(rr[1]); }
;   l_reg = l_reg * alpha + ps;
;     ...
;   PK4(p0, 0, pa0); PK4(p0, 8, pa1); PK4(p1, 0, pa2); PK4(p1, 8, pa3);
;     ...
; }
; template <int DK, bool QL>
; __device__ __forceinline__ void qkt(f32x16& p0, f32x16& p1, const bf16* Ks, const bf16x8* qr, const char* ql, int r32, int hi) {
;   p0 = f32x16{}; p1 = f32x16{};
; #pragma unroll
;   for (int d0 = 0; d0 < DK / 16; ++d0) { int cb = (d0 * 16 + hi * 8) * 2;
;     const bf16x8 qv = QL ? *reinterpret_cast<const bf16x8*>(ql + d0 * 1024) : qr[d0];
;     bf16x8 b0 = *reinterpret_cast<const bf16x8*>((const char*)Ks + kswz<DK>(r32, cb));
;     bf16x8 b1 = *reinterpret_cast<const bf16x8*>((const char*)Ks + kswz<DK>(32 + r32, cb));
;     p0 = __builtin_amdgcn_mfma_f32_32x32x16_bf16(b0, qv, p0, 0, 0, 0);
;     p1 = __builtin_amdgcn_mfma_f32_32x32x16_bf16(b1, qv, p1, 0, 0, 0); }
; }
; template <int OFF> __device__ __forceinline__ s16x4 tr_read(int vb) {
;   s16x4 r; asm volatile("ds_read_b64_tr_b16 %0, %1 offset:%2" : "=&v"(r) : "v"(vb), "i"(OFF) : "memory"); return r;
; }
; template <int D0> __device__ __forceinline__ void pv_one(f32x16& od, int vb, bf16x8 pa0, bf16x8 pa1, bf16x8 pa2, bf16x8 pa3) {
;   const s16x4 l0 = tr_read<v_rd_off(D0, 0, 0)>(vb), h0 = tr_read<v_rd_off(D0, 0, 1)>(vb), l1 = tr_read<v_rd_off(D0, 1, 0)>(vb), h1 = tr_read<v_rd_off(D0, 1, 1)>(vb);
;   const s16x4 l2 = tr_read<v_rd_off(D0, 2, 0)>(vb), h2 = tr_read<v_rd_off(D0, 2, 1)>(vb), l3 = tr_read<v_rd_off(D0, 3, 0)>(vb), h3 = tr_read<v_rd_off(D0, 3, 1)>(vb);
;   asm volatile("s_waitcnt lgkmcnt(0)" ::: "memory"); SBAR();
;     ...
;   od = __builtin_amdgcn_mfma_f32_32x32x16_bf16(pa0, PK(l0, h0), od, 0, 0, 0);
;   od = __builtin_amdgcn_mfma_f32_32x32x16_bf16(pa1, PK(l1, h1), od, 0, 0, 0);
;   od = __builtin_amdgcn_mfma_f32_32x32x16_bf16(pa2, PK(l2, h2), od, 0, 0, 0);
.LBB0_701:
	ds_read_b128 v[66:69], v215 offset:49152
	ds_read_b128 v[70:73], v215 offset:53248
	v_exp_f32_e32 v143, v138
	v_add_f32_e32 v138, v226, v177
	s_waitcnt lgkmcnt(1)
	v_mfma_f32_32x32x16_bf16 v[82:97], v[66:69], v[110:113], 0
	v_add_f32_e32 v138, v161, v138
	v_add_f32_e32 v138, v223, v138
	v_add_f32_e32 v138, v153, v138
	ds_read_b128 v[228:231], v216 offset:49152
	ds_read_b128 v[232:235], v216 offset:53248
	v_add_f32_e32 v138, v176, v138
	v_add_f32_e32 v138, v152, v138
	v_add_f32_e32 v138, v160, v138
	s_waitcnt lgkmcnt(2)
	v_mfma_f32_32x32x16_bf16 v[66:81], v[70:73], v[110:113], 0
	v_add_f32_e32 v138, v149, v138
	v_add_f32_e32 v138, v151, v138
	v_add_f32_e32 v138, v147, v138
	v_add_f32_e32 v138, v150, v138
	v_add_f32_e32 v138, v145, v138
	v_exp_f32_e32 v164, v139
	v_add_f32_e32 v138, v148, v138
	s_waitcnt lgkmcnt(1)
	v_mfma_f32_32x32x16_bf16 v[82:97], v[228:231], v[106:109], v[82:97]
	v_exp_f32_e32 v136, v136
	v_add_f32_e32 v138, v144, v138
	v_exp_f32_e32 v137, v137
	v_add_f32_e32 v138, v146, v138
	v_exp_f32_e32 v130, v130
	v_add_f32_e32 v138, v143, v138
	v_exp_f32_e32 v131, v131
	s_waitcnt lgkmcnt(0)
	v_mfma_f32_32x32x16_bf16 v[66:81], v[232:235], v[106:109], v[66:81]
	ds_read_b128 v[228:231], v217 offset:49152
	ds_read_b128 v[232:235], v217 offset:53248
	v_add_f32_e32 v138, v164, v138
	v_exp_f32_e32 v128, v128
	v_add_f32_e32 v138, v136, v138
	v_exp_f32_e32 v129, v129
	v_add_f32_e32 v138, v137, v138
	v_exp_f32_e32 v126, v126
	s_waitcnt lgkmcnt(1)
	v_mfma_f32_32x32x16_bf16 v[82:97], v[228:231], v[102:105], v[82:97]
	v_add_f32_e32 v138, v130, v138
	v_exp_f32_e32 v127, v127
	v_add_f32_e32 v138, v131, v138
	v_exp_f32_e32 v165, v140
	v_add_f32_e32 v138, v128, v138
	v_exp_f32_e32 v166, v141
	v_add_f32_e32 v138, v129, v138
	s_waitcnt lgkmcnt(0)
	v_mfma_f32_32x32x16_bf16 v[66:81], v[232:235], v[102:105], v[66:81]
	ds_read_b128 v[228:231], v218 offset:49152
	ds_read_b128 v[232:235], v218 offset:53248
	v_exp_f32_e32 v134, v134
	v_add_f32_e32 v138, v126, v138
	v_exp_f32_e32 v135, v135
	v_add_f32_e32 v138, v127, v138
	v_exp_f32_e32 v132, v132
	v_add_f32_e32 v138, v165, v138
	s_waitcnt lgkmcnt(1)
	v_mfma_f32_32x32x16_bf16 v[82:97], v[228:231], v[98:101], v[82:97]
	v_exp_f32_e32 v133, v133
	v_add_f32_e32 v138, v166, v138
	v_add_f32_e32 v138, v134, v138
	v_add_f32_e32 v138, v135, v138
	v_add_f32_e32 v138, v132, v138
	v_add_f32_e32 v220, v133, v138
	s_waitcnt lgkmcnt(0)
	v_mfma_f32_32x32x16_bf16 v[66:81], v[232:235], v[98:101], v[66:81]
	v_cvt_pk_bf16_f32 v138, v177, v226
	v_cvt_pk_bf16_f32 v139, v161, v223
	v_cvt_pk_bf16_f32 v140, v153, v176
	v_cvt_pk_bf16_f32 v141, v152, v160
	v_cvt_pk_bf16_f32 v222, v149, v151
	v_cvt_pk_bf16_f32 v223, v147, v150
	v_cvt_pk_bf16_f32 v224, v145, v148
	v_cvt_pk_bf16_f32 v225, v144, v146
	v_cvt_pk_bf16_f32 v144, v143, v164
	v_cvt_pk_bf16_f32 v145, v136, v137
	v_cvt_pk_bf16_f32 v146, v130, v131
	v_cvt_pk_bf16_f32 v147, v128, v129
	v_cvt_pk_bf16_f32 v148, v126, v127
	v_cvt_pk_bf16_f32 v149, v165, v166
	v_cvt_pk_bf16_f32 v150, v134, v135
	v_cvt_pk_bf16_f32 v151, v132, v133
	global_load_dwordx4 v[182:185], v[178:179], off offset:2048
	global_load_dwordx4 v[194:197], v[180:181], off offset:2048
	global_load_dwordx4 v[134:137], v[204:205], off offset:1152
	s_mov_b32 s4, 0xa0000
	s_mov_b32 s5, 0
	s_nop 0
	v_lshl_add_u64 v[178:179], v[178:179], 0, s[4:5]
	v_lshl_add_u64 v[180:181], v[180:181], 0, s[4:5]
	v_lshl_add_u64 v[204:205], v[204:205], 0, s[4:5]
	ds_read_b64_tr_b16 v[226:227], v211 offset:0
	ds_read_b64_tr_b16 v[228:229], v211 offset:0x800
	ds_read_b64_tr_b16 v[230:231], v211 offset:0x1000
	ds_read_b64_tr_b16 v[232:233], v211 offset:0x1800
	ds_read_b64_tr_b16 v[234:235], v211 offset:0x2000
	ds_read_b64_tr_b16 v[236:237], v211 offset:0x2800
	ds_read_b64_tr_b16 v[238:239], v211 offset:0x3000
	ds_read_b64_tr_b16 v[240:241], v211 offset:0x3800
	s_waitcnt lgkmcnt(4)
	s_nop 0
	v_mfma_f32_32x32x16_bf16 v[2:17], v[138:141], v[226:229], v[2:17]
	ds_read_b64_tr_b16 v[226:227], v211 offset:0x200
	ds_read_b64_tr_b16 v[228:229], v211 offset:0xa00
	v_mfma_f32_32x32x16_bf16 v[2:17], v[222:225], v[230:233], v[2:17]
	ds_read_b64_tr_b16 v[230:231], v211 offset:0x1200
	ds_read_b64_tr_b16 v[232:233], v211 offset:0x1a00
	s_waitcnt lgkmcnt(4)
	v_mfma_f32_32x32x16_bf16 v[2:17], v[144:147], v[234:237], v[2:17]
	ds_read_b64_tr_b16 v[234:235], v211 offset:0x2200
	ds_read_b64_tr_b16 v[236:237], v211 offset:0x2a00
	v_mfma_f32_32x32x16_bf16 v[2:17], v[148:151], v[238:241], v[2:17]
	ds_read_b64_tr_b16 v[238:239], v211 offset:0x3200
	ds_read_b64_tr_b16 v[240:241], v211 offset:0x3a00
	s_waitcnt lgkmcnt(4)
	v_mfma_f32_32x32x16_bf16 v[50:65], v[138:141], v[226:229], v[50:65]
	ds_read_b64_tr_b16 v[226:227], v211 offset:0x400
	ds_read_b64_tr_b16 v[228:229], v211 offset:0xc00
	v_mfma_f32_32x32x16_bf16 v[50:65], v[222:225], v[230:233], v[50:65]
	ds_read_b64_tr_b16 v[230:231], v211 offset:0x1400
	ds_read_b64_tr_b16 v[232:233], v211 offset:0x1c00
	s_waitcnt lgkmcnt(4)
	v_mfma_f32_32x32x16_bf16 v[50:65], v[144:147], v[234:237], v[50:65]
	ds_read_b64_tr_b16 v[234:235], v211 offset:0x2400
	ds_read_b64_tr_b16 v[236:237], v211 offset:0x2c00
	v_mfma_f32_32x32x16_bf16 v[50:65], v[148:151], v[238:241], v[50:65]
	ds_read_b64_tr_b16 v[238:239], v211 offset:0x3400
	ds_read_b64_tr_b16 v[240:241], v211 offset:0x3c00
	s_waitcnt lgkmcnt(4)
	v_mfma_f32_32x32x16_bf16 v[34:49], v[138:141], v[226:229], v[34:49]
	ds_read_b64_tr_b16 v[226:227], v211 offset:0x600
	ds_read_b64_tr_b16 v[228:229], v211 offset:0xe00
	v_mfma_f32_32x32x16_bf16 v[34:49], v[222:225], v[230:233], v[34:49]
	ds_read_b64_tr_b16 v[230:231], v211 offset:0x1600
	ds_read_b64_tr_b16 v[232:233], v211 offset:0x1e00
	s_waitcnt lgkmcnt(4)
; #define SBAR() __builtin_amdgcn_sched_barrier(0)
; __device__ __forceinline__ void partialSM(f32x16& p0, f32x16& p1, float& m_reg, float& mn, float& alpha, float C, float thrRaw) {
;   float pmax = p0[0];
; #pragma unroll
;   for (int r = 1; r < 16; ++r) pmax = fmaxf(pmax, p0[r]);
; #pragma unroll
;   for (int r = 0; r < 16; ++r) pmax = fmaxf(pmax, p1[r]);
;   { auto rr = __builtin_amdgcn_permlane32_swap(__float_as_uint(pmax), __float_as_uint(pmax), false, false);
;     pmax = fmaxf(__uint_as_float(rr[0]), __uint_as_float(rr[1])); }
;   if (__builtin_expect(__all(pmax - m_reg <= thrRaw), 1)) { mn = m_reg; alpha = 1.f; }
;   else { mn = fmaxf(m_reg, pmax); alpha = __builtin_amdgcn_exp2f((m_reg - mn) * C); m_reg = mn; }
; template <int D0> __device__ __forceinline__ void pv_one(f32x16& od, int vb, bf16x8 pa0, bf16x8 pa1, bf16x8 pa2, bf16x8 pa3) {
;   const s16x4 l0 = tr_read<v_rd_off(D0, 0, 0)>(vb), h0 = tr_read<v_rd_off(D0, 0, 1)>(vb), l1 = tr_read<v_rd_off(D0, 1, 0)>(vb), h1 = tr_read<v_rd_off(D0, 1, 1)>(vb);
;   const s16x4 l2 = tr_read<v_rd_off(D0, 2, 0)>(vb), h2 = tr_read<v_rd_off(D0, 2, 1)>(vb), l3 = tr_read<v_rd_off(D0, 3, 0)>(vb), h3 = tr_read<v_rd_off(D0, 3, 1)>(vb);
;   asm volatile("s_waitcnt lgkmcnt(0)" ::: "memory"); SBAR();
;     ...
;   od = __builtin_amdgcn_mfma_f32_32x32x16_bf16(pa0, PK(l0, h0), od, 0, 0, 0);
;   od = __builtin_amdgcn_mfma_f32_32x32x16_bf16(pa1, PK(l1, h1), od, 0, 0, 0);
;   od = __builtin_amdgcn_mfma_f32_32x32x16_bf16(pa2, PK(l2, h2), od, 0, 0, 0);
;   od = __builtin_amdgcn_mfma_f32_32x32x16_bf16(pa3, PK(l3, h3), od, 0, 0, 0);
;     ...
; }
; __device__ __forceinline__ void pv_d0(f32x16* o, int vb, bf16x8 pa0, bf16x8 pa1, bf16x8 pa2, bf16x8 pa3) {
;   pv_one<0>(o[0], vb, pa0, pa1, pa2, pa3); pv_one<1>(o[1], vb, pa0, pa1, pa2, pa3); pv_one<2>(o[2], vb, pa0, pa1, pa2, pa3); pv_one<3>(o[3], vb, pa0, pa1, pa2, pa3);
	v_mfma_f32_32x32x16_bf16 v[34:49], v[144:147], v[234:237], v[34:49]
	ds_read_b64_tr_b16 v[234:235], v211 offset:0x2600
	ds_read_b64_tr_b16 v[236:237], v211 offset:0x2e00
	v_mfma_f32_32x32x16_bf16 v[34:49], v[148:151], v[238:241], v[34:49]
	ds_read_b64_tr_b16 v[238:239], v211 offset:0x3600
	ds_read_b64_tr_b16 v[240:241], v211 offset:0x3e00
	s_waitcnt lgkmcnt(6)
	v_mfma_f32_32x32x16_bf16 v[18:33], v[138:141], v[226:229], v[18:33]
	v_max_f32_e32 v138, v83, v82
	v_max3_f32 v138, v138, v84, v85
	v_max3_f32 v138, v138, v86, v87
	v_max3_f32 v138, v138, v88, v89
	v_max3_f32 v138, v138, v90, v91
	v_max3_f32 v138, v138, v92, v93
	v_max3_f32 v138, v138, v94, v95
	s_waitcnt lgkmcnt(4)
	v_mfma_f32_32x32x16_bf16 v[18:33], v[222:225], v[230:233], v[18:33]
	v_max3_f32 v138, v138, v96, v97
	v_max3_f32 v138, v138, v66, v67
	v_max3_f32 v138, v138, v68, v69
	v_max3_f32 v138, v138, v70, v71
	v_max3_f32 v138, v138, v72, v73
	v_max3_f32 v138, v138, v74, v75
	v_max3_f32 v138, v138, v76, v77
	v_max3_f32 v138, v138, v78, v79
	s_waitcnt lgkmcnt(2)
	v_mfma_f32_32x32x16_bf16 v[18:33], v[144:147], v[234:237], v[18:33]
	v_max3_f32 v138, v138, v80, v81
	v_mov_b32_e32 v139, v138
	s_nop 1
	v_permlane32_swap_b32_e32 v138, v139
	v_max_f32_e32 v138, v139, v138
	v_sub_f32_e32 v139, v138, v142
	s_mov_b32 s2, 0x42800000
	v_cmp_ge_f32_e32 vcc, s2, v139
	v_max_f32_e32 v138, v142, v138
	s_waitcnt lgkmcnt(0)
	v_mfma_f32_32x32x16_bf16 v[18:33], v[148:151], v[238:241], v[18:33]
	v_sub_f32_e32 v139, v142, v138
	v_mul_f32_e32 v139, 0x3e38aa3b, v139
	v_exp_f32_e32 v139, v139
	s_cmp_eq_u64 vcc, exec
	s_cselect_b64 s[2:3], -1, 0
	s_waitcnt vmcnt(3)
	v_cndmask_b32_e64 v222, v139, 1.0, s[2:3]
	v_cmp_gt_f32_e32 vcc, 1.0, v222
	ds_write_b128 v214, v[122:125] offset:32768
	s_cbranch_vccz .LBB0_705
	s_and_saveexec_b64 s[4:5], s[0:1]
	ds_write_b32 v208, v222 offset:128
	s_or_b64 exec, exec, s[4:5]
	s_waitcnt lgkmcnt(0)
	v_add_u32_e32 v139, v207, v0
	ds_read_b128 v[144:147], v139 offset:224
	ds_read_b128 v[148:151], v139 offset:192
	ds_read_b128 v[224:227], v139 offset:160
	ds_read_b128 v[228:231], v139 offset:128
	s_waitcnt lgkmcnt(3)
	v_pk_mul_f32 v[14:15], v[14:15], v[144:145]
	s_waitcnt lgkmcnt(2)
	v_pk_mul_f32 v[10:11], v[10:11], v[148:149]
	s_waitcnt lgkmcnt(1)
	v_pk_mul_f32 v[6:7], v[6:7], v[224:225]
	v_pk_mul_f32 v[16:17], v[16:17], v[146:147]
	v_pk_mul_f32 v[12:13], v[12:13], v[150:151]
	v_pk_mul_f32 v[8:9], v[8:9], v[226:227]
	s_waitcnt lgkmcnt(0)
	v_pk_mul_f32 v[4:5], v[4:5], v[230:231]
	v_pk_mul_f32 v[2:3], v[2:3], v[228:229]
	v_pk_mul_f32 v[62:63], v[144:145], v[62:63]
	v_pk_mul_f32 v[58:59], v[148:149], v[58:59]
	v_pk_mul_f32 v[54:55], v[224:225], v[54:55]
	v_pk_mul_f32 v[64:65], v[146:147], v[64:65]
	v_pk_mul_f32 v[60:61], v[150:151], v[60:61]
	v_pk_mul_f32 v[56:57], v[226:227], v[56:57]
	v_pk_mul_f32 v[52:53], v[230:231], v[52:53]
	v_pk_mul_f32 v[50:51], v[228:229], v[50:51]
	v_pk_mul_f32 v[46:47], v[144:145], v[46:47]
	v_pk_mul_f32 v[42:43], v[148:149], v[42:43]
	v_pk_mul_f32 v[38:39], v[224:225], v[38:39]
	v_pk_mul_f32 v[48:49], v[146:147], v[48:49]
	v_pk_mul_f32 v[44:45], v[150:151], v[44:45]
	v_pk_mul_f32 v[40:41], v[226:227], v[40:41]
	v_pk_mul_f32 v[36:37], v[230:231], v[36:37]
	v_pk_mul_f32 v[34:35], v[228:229], v[34:35]
	v_pk_mul_f32 v[30:31], v[144:145], v[30:31]
	v_pk_mul_f32 v[26:27], v[148:149], v[26:27]
	v_pk_mul_f32 v[22:23], v[224:225], v[22:23]
	v_pk_mul_f32 v[32:33], v[146:147], v[32:33]
	v_pk_mul_f32 v[28:29], v[150:151], v[28:29]
	v_pk_mul_f32 v[24:25], v[226:227], v[24:25]
	v_pk_mul_f32 v[20:21], v[230:231], v[20:21]
	v_pk_mul_f32 v[18:19], v[228:229], v[18:19]
; __device__ __forceinline__ void partialSM(f32x16& p0, f32x16& p1, float& m_reg, float& mn, float& alpha, float C, float thrRaw) {
;     ...
;   float mnC = -mn * C;
; #pragma unroll
;   for (int r = 0; r < 16; ++r) p0[r] = fmaf(p0[r], C, mnC);
; #pragma unroll
;   for (int r = 0; r < 16; ++r) p1[r] = fmaf(p1[r], C, mnC);
; #pragma unroll
;   for (int r = 0; r < 16; ++r) p0[r] = __builtin_amdgcn_exp2f(p0[r]);
; }
; __device__ __forceinline__ void finishSM(f32x16& p0, f32x16& p1, float alpha, float& l_reg, bf16x8& pa0, bf16x8& pa1, bf16x8& pa2, bf16x8& pa3) {
; #pragma unroll
;   for (int r = 0; r < 16; ++r) p1[r] = __builtin_amdgcn_exp2f(p1[r]);
;   float ps = 0;
; #pragma unroll
;   for (int r = 0; r < 16; ++r) ps += p0[r];
; #pragma unroll
;   for (int r = 0; r < 16; ++r) ps += p1[r];
;   { auto rr = __builtin_amdgcn_permlane32_swap(__float_as_uint(ps), __float_as_uint(ps), false, false);
;     ps = __uint_as_float(rr[0]) + __uint_as_float(rr[1]); }
;   l_reg = l_reg * alpha + ps;
;     ...
;   PK4(p0, 0, pa0); PK4(p0, 8, pa1); PK4(p1, 0, pa2); PK4(p1, 8, pa3);
;     ...
; }
; template <int DK, bool QL>
; __device__ __forceinline__ void qkt(f32x16& p0, f32x16& p1, const bf16* Ks, const bf16x8* qr, const char* ql, int r32, int hi) {
;   p0 = f32x16{}; p1 = f32x16{};
; #pragma unroll
;   for (int d0 = 0; d0 < DK / 16; ++d0) { int cb = (d0 * 16 + hi * 8) * 2;
;     const bf16x8 qv = QL ? *reinterpret_cast<const bf16x8*>(ql + d0 * 1024) : qr[d0];
;     bf16x8 b0 = *reinterpret_cast<const bf16x8*>((const char*)Ks + kswz<DK>(r32, cb));
;     bf16x8 b1 = *reinterpret_cast<const bf16x8*>((const char*)Ks + kswz<DK>(32 + r32, cb));
;     p0 = __builtin_amdgcn_mfma_f32_32x32x16_bf16(b0, qv, p0, 0, 0, 0);
;     p1 = __builtin_amdgcn_mfma_f32_32x32x16_bf16(b1, qv, p1, 0, 0, 0); }
; }
.LBB0_705:
	v_cndmask_b32_e64 v223, v138, v142, s[2:3]
	v_mul_f32_e32 v224, 0xbe38aa3b, v223
	s_mov_b32 s2, 0x3e38aa3b
	v_pk_fma_f32 v[82:83], v[82:83], s[2:3], v[224:225] op_sel_hi:[1,0,0]
	v_pk_fma_f32 v[84:85], v[84:85], s[2:3], v[224:225] op_sel_hi:[1,0,0]
	v_pk_fma_f32 v[86:87], v[86:87], s[2:3], v[224:225] op_sel_hi:[1,0,0]
	v_pk_fma_f32 v[88:89], v[88:89], s[2:3], v[224:225] op_sel_hi:[1,0,0]
	v_pk_fma_f32 v[90:91], v[90:91], s[2:3], v[224:225] op_sel_hi:[1,0,0]
	v_pk_fma_f32 v[92:93], v[92:93], s[2:3], v[224:225] op_sel_hi:[1,0,0]
	v_pk_fma_f32 v[94:95], v[94:95], s[2:3], v[224:225] op_sel_hi:[1,0,0]
	v_pk_fma_f32 v[96:97], v[96:97], s[2:3], v[224:225] op_sel_hi:[1,0,0]
	v_exp_f32_e32 v138, v82
	v_exp_f32_e32 v153, v83
	v_exp_f32_e32 v139, v84
	v_exp_f32_e32 v152, v85
	v_exp_f32_e32 v140, v86
	v_exp_f32_e32 v151, v87
	v_exp_f32_e32 v141, v88
	v_exp_f32_e32 v150, v89
	v_exp_f32_e32 v142, v90
	v_exp_f32_e32 v149, v91
	v_exp_f32_e32 v143, v92
	v_exp_f32_e32 v148, v93
	v_exp_f32_e32 v144, v94
	v_exp_f32_e32 v147, v95
	v_exp_f32_e32 v145, v96
	v_exp_f32_e32 v146, v97
	v_fmamk_f32 v233, v66, 0x3e38aa3b, v224
	v_fmamk_f32 v234, v67, 0x3e38aa3b, v224
	v_fmamk_f32 v235, v68, 0x3e38aa3b, v224
	v_fmamk_f32 v236, v69, 0x3e38aa3b, v224
	v_fmamk_f32 v237, v70, 0x3e38aa3b, v224
	v_fmamk_f32 v226, v71, 0x3e38aa3b, v224
	v_fmamk_f32 v227, v72, 0x3e38aa3b, v224
	v_fmamk_f32 v228, v73, 0x3e38aa3b, v224
	v_fmamk_f32 v229, v74, 0x3e38aa3b, v224
	v_fmamk_f32 v230, v75, 0x3e38aa3b, v224
	v_fmamk_f32 v231, v76, 0x3e38aa3b, v224
	v_fmamk_f32 v232, v77, 0x3e38aa3b, v224
	v_fmamk_f32 v225, v78, 0x3e38aa3b, v224
	v_fmamk_f32 v238, v79, 0x3e38aa3b, v224
	v_fmamk_f32 v239, v80, 0x3e38aa3b, v224
	v_fmac_f32_e32 v224, 0x3e38aa3b, v81
	s_waitcnt lgkmcnt(0)
	s_barrier
	ds_write_b128 v212, v[114:117]
	ds_write_b128 v213, v[118:121]
	ds_read_b128 v[66:69], v215 offset:32768
	ds_read_b128 v[70:73], v215 offset:36864
	v_exp_f32_e32 v164, v233
	v_exp_f32_e32 v233, v224
	v_add_f32_e32 v224, v153, v138
	s_waitcnt lgkmcnt(1)
	v_mfma_f32_32x32x16_bf16 v[82:97], v[66:69], v[110:113], 0
	v_add_f32_e32 v224, v139, v224
	v_add_f32_e32 v224, v152, v224
	v_add_f32_e32 v224, v140, v224
	ds_read_b128 v[240:243], v216 offset:32768
	ds_read_b128 v[244:247], v216 offset:36864
	v_add_f32_e32 v224, v151, v224
	v_add_f32_e32 v224, v141, v224
	v_add_f32_e32 v224, v150, v224
	s_waitcnt lgkmcnt(2)
	v_mfma_f32_32x32x16_bf16 v[66:81], v[70:73], v[110:113], 0
	v_add_f32_e32 v224, v142, v224
	v_add_f32_e32 v224, v149, v224
	v_add_f32_e32 v224, v143, v224
	v_add_f32_e32 v224, v148, v224
	v_add_f32_e32 v224, v144, v224
	v_exp_f32_e32 v165, v234
	v_add_f32_e32 v224, v147, v224
	s_waitcnt lgkmcnt(1)
	v_mfma_f32_32x32x16_bf16 v[82:97], v[240:243], v[106:109], v[82:97]
	v_exp_f32_e32 v166, v235
	v_add_f32_e32 v224, v145, v224
	v_exp_f32_e32 v167, v236
	v_add_f32_e32 v224, v146, v224
	v_exp_f32_e32 v172, v237
	v_add_f32_e32 v224, v164, v224
	v_exp_f32_e32 v173, v226
	s_waitcnt lgkmcnt(0)
	v_mfma_f32_32x32x16_bf16 v[66:81], v[244:247], v[106:109], v[66:81]
	ds_read_b128 v[240:243], v217 offset:32768
	ds_read_b128 v[244:247], v217 offset:36864
	v_add_f32_e32 v224, v165, v224
	v_exp_f32_e32 v174, v227
	v_add_f32_e32 v224, v166, v224
	v_exp_f32_e32 v175, v228
	v_add_f32_e32 v224, v167, v224
	v_exp_f32_e32 v226, v229
	s_waitcnt lgkmcnt(1)
	v_mfma_f32_32x32x16_bf16 v[82:97], v[240:243], v[102:105], v[82:97]
	v_add_f32_e32 v224, v172, v224
	v_exp_f32_e32 v227, v230
	v_add_f32_e32 v224, v173, v224
	v_exp_f32_e32 v228, v231
	v_add_f32_e32 v224, v174, v224
	v_exp_f32_e32 v229, v232
	v_add_f32_e32 v224, v175, v224
	s_waitcnt lgkmcnt(0)
	v_mfma_f32_32x32x16_bf16 v[66:81], v[244:247], v[102:105], v[66:81]
	ds_read_b128 v[240:243], v218 offset:32768
	ds_read_b128 v[244:247], v218 offset:36864
	v_exp_f32_e32 v230, v225
	v_add_f32_e32 v224, v226, v224
	v_exp_f32_e32 v231, v238
	v_add_f32_e32 v224, v227, v224
	v_exp_f32_e32 v232, v239
	v_add_f32_e32 v224, v228, v224
	s_waitcnt lgkmcnt(1)
	v_mfma_f32_32x32x16_bf16 v[82:97], v[240:243], v[98:101], v[82:97]
	v_add_f32_e32 v224, v229, v224
	v_add_f32_e32 v224, v230, v224
	v_add_f32_e32 v224, v231, v224
	v_add_f32_e32 v224, v232, v224
	v_add_f32_e32 v224, v233, v224
	v_cvt_pk_bf16_f32 v138, v138, v153
	s_waitcnt lgkmcnt(0)
	v_mfma_f32_32x32x16_bf16 v[66:81], v[244:247], v[98:101], v[66:81]
	v_cvt_pk_bf16_f32 v139, v139, v152
	v_cvt_pk_bf16_f32 v140, v140, v151
	v_cvt_pk_bf16_f32 v141, v141, v150
	v_cvt_pk_bf16_f32 v142, v142, v149
	v_cvt_pk_bf16_f32 v143, v143, v148
	v_cvt_pk_bf16_f32 v144, v144, v147
	v_cvt_pk_bf16_f32 v145, v145, v146
	v_cvt_pk_bf16_f32 v146, v164, v165
	v_cvt_pk_bf16_f32 v147, v166, v167
	v_cvt_pk_bf16_f32 v148, v172, v173
	v_cvt_pk_bf16_f32 v149, v174, v175
	v_cvt_pk_bf16_f32 v150, v226, v227
	v_cvt_pk_bf16_f32 v151, v228, v229
	v_cvt_pk_bf16_f32 v152, v230, v231
	v_cvt_pk_bf16_f32 v153, v232, v233
	s_cmp_gt_u32 s8, 60
	s_cselect_b64 s[4:5], -1, 0
	s_and_b64 vcc, exec, s[4:5]
	s_cbranch_vccnz .Lod_d2
	global_load_dwordx4 v[114:117], v[178:179], off offset:2048
	global_load_dwordx4 v[118:121], v[180:181], off offset:2048
	global_load_dwordx4 v[122:125], v[204:205], off offset:1152
	s_mov_b32 s6, 0xa0000
	s_mov_b32 s7, 0
	s_nop 0
	v_lshl_add_u64 v[178:179], v[178:179], 0, s[6:7]
	v_lshl_add_u64 v[180:181], v[180:181], 0, s[6:7]
	v_lshl_add_u64 v[204:205], v[204:205], 0, s[6:7]

; __device__ __forceinline__ void partialSM(f32x16& p0, f32x16& p1, float& m_reg, float& mn, float& alpha, float C, float thrRaw) {
;     ...
;   float mnC = -mn * C;
; #pragma unroll
;   for (int r = 0; r < 16; ++r) p0[r] = fmaf(p0[r], C, mnC);
; #pragma unroll
;   for (int r = 0; r < 16; ++r) p1[r] = fmaf(p1[r], C, mnC);
; #pragma unroll
;   for (int r = 0; r < 16; ++r) p0[r] = __builtin_amdgcn_exp2f(p0[r]);
; }
; __device__ __forceinline__ void finishSM(f32x16& p0, f32x16& p1, float alpha, float& l_reg, bf16x8& pa0, bf16x8& pa1, bf16x8& pa2, bf16x8& pa3) {
; #pragma unroll
;   for (int r = 0; r < 16; ++r) p1[r] = __builtin_amdgcn_exp2f(p1[r]);
;   float ps = 0;
; #pragma unroll
;   for (int r = 0; r < 16; ++r) ps += p0[r];
; #pragma unroll
;   for (int r = 0; r < 16; ++r) ps += p1[r];
;   { auto rr = __builtin_amdgcn_permlane32_swap(__float_as_uint(ps), __float_as_uint(ps), false, false);
;     ps = __uint_as_float(rr[0]) + __uint_as_float(rr[1]); }
;   l_reg = l_reg * alpha + ps;
.LBB0_711:
	v_cndmask_b32_e64 v142, v138, v223, s[2:3]
	v_mul_f32_e32 v132, 0xbe38aa3b, v142
	v_mov_b32_e32 v133, v132
	s_mov_b32 s2, 0x3e38aa3b
	v_pk_fma_f32 v[82:83], v[82:83], s[2:3], v[132:133] op_sel_hi:[1,0,0]
	v_pk_fma_f32 v[84:85], v[84:85], s[2:3], v[132:133] op_sel_hi:[1,0,0]
	v_pk_fma_f32 v[86:87], v[86:87], s[2:3], v[132:133] op_sel_hi:[1,0,0]
	v_pk_fma_f32 v[88:89], v[88:89], s[2:3], v[132:133] op_sel_hi:[1,0,0]
	v_pk_fma_f32 v[90:91], v[90:91], s[2:3], v[132:133] op_sel_hi:[1,0,0]
	v_pk_fma_f32 v[92:93], v[92:93], s[2:3], v[132:133] op_sel_hi:[1,0,0]
	v_pk_fma_f32 v[94:95], v[94:95], s[2:3], v[132:133] op_sel_hi:[1,0,0]
	v_fmamk_f32 v96, v96, 0x3e38aa3b, v132
	v_fmac_f32_e32 v133, 0x3e38aa3b, v97
	s_mov_b32 s2, 0x3e38aa3b
	v_exp_f32_e32 v177, v82
	v_exp_f32_e32 v226, v83
	v_exp_f32_e32 v161, v84
	v_exp_f32_e32 v223, v85
	v_exp_f32_e32 v153, v86
	v_exp_f32_e32 v176, v87
	v_exp_f32_e32 v152, v88
	v_exp_f32_e32 v160, v89
	v_exp_f32_e32 v149, v90
	v_exp_f32_e32 v151, v91
	v_exp_f32_e32 v147, v92
	v_exp_f32_e32 v150, v93
	v_exp_f32_e32 v145, v94
	v_exp_f32_e32 v148, v95
	v_exp_f32_e32 v144, v96
	v_exp_f32_e32 v146, v133
	v_pk_fma_f32 v[138:139], v[66:67], s[2:3], v[132:133] op_sel_hi:[1,0,0]
	v_pk_fma_f32 v[136:137], v[68:69], s[2:3], v[132:133] op_sel_hi:[1,0,0]
	v_pk_fma_f32 v[130:131], v[70:71], s[2:3], v[132:133] op_sel_hi:[1,0,0]
	v_pk_fma_f32 v[128:129], v[72:73], s[2:3], v[132:133] op_sel_hi:[1,0,0]
	v_pk_fma_f32 v[126:127], v[74:75], s[2:3], v[132:133] op_sel_hi:[1,0,0]
	v_pk_fma_f32 v[140:141], v[76:77], s[2:3], v[132:133] op_sel_hi:[1,0,0]
	v_pk_fma_f32 v[134:135], v[78:79], s[2:3], v[132:133] op_sel_hi:[1,0,0]
	v_pk_fma_f32 v[132:133], v[80:81], s[2:3], v[132:133] op_sel_hi:[1,0,0]
	v_fma_f32 v66, v219, v209, v220
	v_fma_f32 v209, v66, v222, v224
	s_add_i32 s8, s8, 2
	s_and_b64 vcc, exec, s[4:5]
	s_waitcnt lgkmcnt(0)
	s_barrier
	s_cbranch_vccnz .LBB0_713
	v_mov_b32_e32 v219, v143
	ds_write_b128 v212, v[182:185] offset:16384
	ds_write_b128 v213, v[194:197] offset:16384
	s_branch .LBB0_701

; #define SBAR() __builtin_amdgcn_sched_barrier(0)
; #define HOOK(P0, P1, j) do { if (NA) na_hook(P0, P1, krow0 + (j), q_row, q_col, win_r, win_c, rpb, inv_scale, hi); } while (0)
; __device__ __forceinline__ void finishSM(f32x16& p0, f32x16& p1, float alpha, float& l_reg, bf16x8& pa0, bf16x8& pa1, bf16x8& pa2, bf16x8& pa3) {
; #pragma unroll
;   for (int r = 0; r < 16; ++r) p1[r] = __builtin_amdgcn_exp2f(p1[r]);
;   float ps = 0;
; #pragma unroll
;   for (int r = 0; r < 16; ++r) ps += p0[r];
; #pragma unroll
;   for (int r = 0; r < 16; ++r) ps += p1[r];
;   { auto rr = __builtin_amdgcn_permlane32_swap(__float_as_uint(ps), __float_as_uint(ps), false, false);
;     ps = __uint_as_float(rr[0]) + __uint_as_float(rr[1]); }
;   l_reg = l_reg * alpha + ps;
;     ...
;   PK4(p0, 0, pa0); PK4(p0, 8, pa1); PK4(p1, 0, pa2); PK4(p1, 8, pa3);
;     ...
; }
; template <int DK, bool QL>
; __device__ __forceinline__ void qkt(f32x16& p0, f32x16& p1, const bf16* Ks, const bf16x8* qr, const char* ql, int r32, int hi) {
;   p0 = f32x16{}; p1 = f32x16{};
; #pragma unroll
;   for (int d0 = 0; d0 < DK / 16; ++d0) { int cb = (d0 * 16 + hi * 8) * 2;
;     const bf16x8 qv = QL ? *reinterpret_cast<const bf16x8*>(ql + d0 * 1024) : qr[d0];
;     bf16x8 b0 = *reinterpret_cast<const bf16x8*>((const char*)Ks + kswz<DK>(r32, cb));
;     bf16x8 b1 = *reinterpret_cast<const bf16x8*>((const char*)Ks + kswz<DK>(32 + r32, cb));
;     p0 = __builtin_amdgcn_mfma_f32_32x32x16_bf16(b0, qv, p0, 0, 0, 0);
;     p1 = __builtin_amdgcn_mfma_f32_32x32x16_bf16(b1, qv, p1, 0, 0, 0); }
; }
; template <int DK, bool NA, bool QL, int SD> ...
;     ...
;   SBAR(); qkt<DK, QL>(pB0, pB1, (bf16*)((char*)K_lds + SHM_K), qr, ql, r32, hi); HOOK(pB0, pB1, NT - 1);
;   finishSM(pA0, pA1, alA, l_reg, pa0, pa1, pa2, pa3); SBAR();
;   pv_d0(o, vb0, pa0, pa1, pa2, pa3); partialSM(pB0, pB1, m_reg, mnB, alB, C, thrRaw);
.LBB0_713:
	v_mov_b32_e32 v221, v209
	s_nop 1
	v_permlane32_swap_b32_e32 v209, v221
	v_add_f32_e32 v209, v209, v221
	ds_write_b128 v212, v[182:185] offset:16384
	ds_write_b128 v213, v[194:197] offset:16384
	ds_read_b128 v[66:69], v215 offset:49152
	ds_read_b128 v[70:73], v215 offset:53248
	v_exp_f32_e32 v118, v140
	v_exp_f32_e32 v119, v141
	v_exp_f32_e32 v120, v134
	s_waitcnt lgkmcnt(1)
	v_mfma_f32_32x32x16_bf16 v[82:97], v[66:69], v[110:113], 0
	v_exp_f32_e32 v121, v135
	v_exp_f32_e32 v122, v132
	v_exp_f32_e32 v123, v133
	s_waitcnt lgkmcnt(0)
	v_mfma_f32_32x32x16_bf16 v[66:81], v[70:73], v[110:113], 0
	ds_read_b128 v[110:113], v216 offset:49152
	ds_read_b128 v[114:117], v216 offset:53248
	s_waitcnt lgkmcnt(1)
	v_mfma_f32_32x32x16_bf16 v[82:97], v[110:113], v[106:109], v[82:97]
	s_waitcnt lgkmcnt(0)
	v_mfma_f32_32x32x16_bf16 v[66:81], v[114:117], v[106:109], v[66:81]
	ds_read_b128 v[106:109], v217 offset:49152
	ds_read_b128 v[110:113], v217 offset:53248
	v_exp_f32_e32 v114, v128
	v_exp_f32_e32 v115, v129
	v_exp_f32_e32 v116, v126
	v_exp_f32_e32 v117, v127
	s_waitcnt lgkmcnt(1)
	v_mfma_f32_32x32x16_bf16 v[82:97], v[106:109], v[102:105], v[82:97]
	s_waitcnt lgkmcnt(0)
	v_mfma_f32_32x32x16_bf16 v[66:81], v[110:113], v[102:105], v[66:81]
	ds_read_b128 v[102:105], v218 offset:49152
	ds_read_b128 v[106:109], v218 offset:53248
	v_exp_f32_e32 v110, v136
	v_exp_f32_e32 v111, v137
	v_exp_f32_e32 v112, v130
	v_exp_f32_e32 v113, v131
	s_waitcnt lgkmcnt(1)
	v_mfma_f32_32x32x16_bf16 v[82:97], v[102:105], v[98:101], v[82:97]
	s_waitcnt lgkmcnt(0)
	v_mfma_f32_32x32x16_bf16 v[66:81], v[106:109], v[98:101], v[66:81]
	v_add_f32_e32 v98, 0, v177
	v_add_f32_e32 v98, v226, v98
	v_add_f32_e32 v98, v161, v98
	v_add_f32_e32 v98, v223, v98
	v_add_f32_e32 v98, v153, v98
	v_add_f32_e32 v98, v176, v98
	v_add_f32_e32 v98, v152, v98
	v_add_f32_e32 v98, v160, v98
	v_add_f32_e32 v98, v149, v98
	v_add_f32_e32 v98, v151, v98
	v_add_f32_e32 v98, v147, v98
	v_add_f32_e32 v98, v150, v98
	v_exp_f32_e32 v108, v138
	v_add_f32_e32 v98, v145, v98
	v_exp_f32_e32 v109, v139
	v_add_f32_e32 v98, v148, v98
	v_add_f32_e32 v98, v144, v98
	v_add_f32_e32 v98, v146, v98
	v_add_f32_e32 v98, v108, v98
	v_add_f32_e32 v98, v109, v98
	v_add_f32_e32 v98, v110, v98
	v_add_f32_e32 v98, v111, v98
	v_add_f32_e32 v98, v112, v98
	v_add_f32_e32 v98, v113, v98
	v_add_f32_e32 v98, v114, v98
	v_add_f32_e32 v98, v115, v98
	v_add_f32_e32 v98, v116, v98
	v_add_f32_e32 v98, v117, v98
	v_add_f32_e32 v98, v118, v98
	v_add_f32_e32 v98, v119, v98
	v_add_f32_e32 v98, v120, v98
	v_add_f32_e32 v98, v121, v98
	v_add_f32_e32 v98, v122, v98
	v_add_f32_e32 v98, v123, v98
	v_mov_b32_e32 v99, v98
	v_cvt_pk_bf16_f32 v100, v177, v226
	v_cvt_pk_bf16_f32 v101, v161, v223
	v_cvt_pk_bf16_f32 v102, v153, v176
	v_cvt_pk_bf16_f32 v103, v152, v160
	s_nop 1
	v_permlane32_swap_b32_e32 v98, v99
	v_cvt_pk_bf16_f32 v104, v149, v151
	v_cvt_pk_bf16_f32 v105, v147, v150
	v_cvt_pk_bf16_f32 v106, v145, v148
	v_cvt_pk_bf16_f32 v107, v144, v146
	v_cvt_pk_bf16_f32 v108, v108, v109
	v_cvt_pk_bf16_f32 v109, v110, v111
	v_cvt_pk_bf16_f32 v110, v112, v113
	v_cvt_pk_bf16_f32 v111, v114, v115
	v_cvt_pk_bf16_f32 v112, v116, v117
	v_cvt_pk_bf16_f32 v113, v118, v119
	v_cvt_pk_bf16_f32 v114, v120, v121
	v_cvt_pk_bf16_f32 v115, v122, v123
	s_nop 0
	ds_read_b64_tr_b16 v[116:117], v211 offset:0
	ds_read_b64_tr_b16 v[118:119], v211 offset:0x800
	ds_read_b64_tr_b16 v[120:121], v211 offset:0x1000
	ds_read_b64_tr_b16 v[122:123], v211 offset:0x1800
	ds_read_b64_tr_b16 v[124:125], v211 offset:0x2000
	ds_read_b64_tr_b16 v[126:127], v211 offset:0x2800
	ds_read_b64_tr_b16 v[128:129], v211 offset:0x3000
	ds_read_b64_tr_b16 v[130:131], v211 offset:0x3800
	s_waitcnt lgkmcnt(0)
	s_nop 0
	v_mfma_f32_32x32x16_bf16 v[2:17], v[100:103], v[116:119], v[2:17]
	ds_read_b64_tr_b16 v[116:117], v211 offset:0x200
	ds_read_b64_tr_b16 v[118:119], v211 offset:0xa00
	v_mfma_f32_32x32x16_bf16 v[2:17], v[104:107], v[120:123], v[2:17]
	ds_read_b64_tr_b16 v[120:121], v211 offset:0x1200
	ds_read_b64_tr_b16 v[122:123], v211 offset:0x1a00
	v_mfma_f32_32x32x16_bf16 v[2:17], v[108:111], v[124:127], v[2:17]
	ds_read_b64_tr_b16 v[124:125], v211 offset:0x2200
	ds_read_b64_tr_b16 v[126:127], v211 offset:0x2a00
	v_mfma_f32_32x32x16_bf16 v[2:17], v[112:115], v[128:131], v[2:17]
	ds_read_b64_tr_b16 v[128:129], v211 offset:0x3200
	ds_read_b64_tr_b16 v[130:131], v211 offset:0x3a00
	s_waitcnt lgkmcnt(0)
; #define SBAR() __builtin_amdgcn_sched_barrier(0)
; __device__ __forceinline__ void partialSM(f32x16& p0, f32x16& p1, float& m_reg, float& mn, float& alpha, float C, float thrRaw) {
;   float pmax = p0[0];
; #pragma unroll
;   for (int r = 1; r < 16; ++r) pmax = fmaxf(pmax, p0[r]);
; #pragma unroll
;   for (int r = 0; r < 16; ++r) pmax = fmaxf(pmax, p1[r]);
;   { auto rr = __builtin_amdgcn_permlane32_swap(__float_as_uint(pmax), __float_as_uint(pmax), false, false);
;     pmax = fmaxf(__uint_as_float(rr[0]), __uint_as_float(rr[1])); }
;   if (__builtin_expect(__all(pmax - m_reg <= thrRaw), 1)) { mn = m_reg; alpha = 1.f; }
;   else { mn = fmaxf(m_reg, pmax); alpha = __builtin_amdgcn_exp2f((m_reg - mn) * C); m_reg = mn; }
; template <int D0> __device__ __forceinline__ void pv_one(f32x16& od, int vb, bf16x8 pa0, bf16x8 pa1, bf16x8 pa2, bf16x8 pa3) {
;   const s16x4 l0 = tr_read<v_rd_off(D0, 0, 0)>(vb), h0 = tr_read<v_rd_off(D0, 0, 1)>(vb), l1 = tr_read<v_rd_off(D0, 1, 0)>(vb), h1 = tr_read<v_rd_off(D0, 1, 1)>(vb);
;   const s16x4 l2 = tr_read<v_rd_off(D0, 2, 0)>(vb), h2 = tr_read<v_rd_off(D0, 2, 1)>(vb), l3 = tr_read<v_rd_off(D0, 3, 0)>(vb), h3 = tr_read<v_rd_off(D0, 3, 1)>(vb);
;   asm volatile("s_waitcnt lgkmcnt(0)" ::: "memory"); SBAR();
;     ...
;   od = __builtin_amdgcn_mfma_f32_32x32x16_bf16(pa0, PK(l0, h0), od, 0, 0, 0);
;   od = __builtin_amdgcn_mfma_f32_32x32x16_bf16(pa1, PK(l1, h1), od, 0, 0, 0);
;   od = __builtin_amdgcn_mfma_f32_32x32x16_bf16(pa2, PK(l2, h2), od, 0, 0, 0);
;   od = __builtin_amdgcn_mfma_f32_32x32x16_bf16(pa3, PK(l3, h3), od, 0, 0, 0);
;     ...
; }
; __device__ __forceinline__ void pv_d0(f32x16* o, int vb, bf16x8 pa0, bf16x8 pa1, bf16x8 pa2, bf16x8 pa3) {
;   pv_one<0>(o[0], vb, pa0, pa1, pa2, pa3); pv_one<1>(o[1], vb, pa0, pa1, pa2, pa3); pv_one<2>(o[2], vb, pa0, pa1, pa2, pa3); pv_one<3>(o[3], vb, pa0, pa1, pa2, pa3);
	v_mfma_f32_32x32x16_bf16 v[50:65], v[100:103], v[116:119], v[50:65]
	ds_read_b64_tr_b16 v[116:117], v211 offset:0x400
	ds_read_b64_tr_b16 v[118:119], v211 offset:0xc00
	v_mfma_f32_32x32x16_bf16 v[50:65], v[104:107], v[120:123], v[50:65]
	ds_read_b64_tr_b16 v[120:121], v211 offset:0x1400
	ds_read_b64_tr_b16 v[122:123], v211 offset:0x1c00
	v_mfma_f32_32x32x16_bf16 v[50:65], v[108:111], v[124:127], v[50:65]
	ds_read_b64_tr_b16 v[124:125], v211 offset:0x2400
	ds_read_b64_tr_b16 v[126:127], v211 offset:0x2c00
	v_mfma_f32_32x32x16_bf16 v[50:65], v[112:115], v[128:131], v[50:65]
	ds_read_b64_tr_b16 v[128:129], v211 offset:0x3400
	ds_read_b64_tr_b16 v[130:131], v211 offset:0x3c00
	s_waitcnt lgkmcnt(0)
	v_mfma_f32_32x32x16_bf16 v[34:49], v[100:103], v[116:119], v[34:49]
	ds_read_b64_tr_b16 v[116:117], v211 offset:0x600
	ds_read_b64_tr_b16 v[118:119], v211 offset:0xe00
	v_mfma_f32_32x32x16_bf16 v[34:49], v[104:107], v[120:123], v[34:49]
	ds_read_b64_tr_b16 v[120:121], v211 offset:0x1600
	ds_read_b64_tr_b16 v[122:123], v211 offset:0x1e00
	v_mfma_f32_32x32x16_bf16 v[34:49], v[108:111], v[124:127], v[34:49]
	ds_read_b64_tr_b16 v[124:125], v211 offset:0x2600
	ds_read_b64_tr_b16 v[126:127], v211 offset:0x2e00
	v_mfma_f32_32x32x16_bf16 v[34:49], v[112:115], v[128:131], v[34:49]
	ds_read_b64_tr_b16 v[128:129], v211 offset:0x3600
	ds_read_b64_tr_b16 v[130:131], v211 offset:0x3e00
	s_waitcnt lgkmcnt(0)
	v_mfma_f32_32x32x16_bf16 v[18:33], v[100:103], v[116:119], v[18:33]
	v_max_f32_e32 v100, v83, v83
	v_max_f32_e32 v101, v82, v82
	v_max_f32_e32 v100, v101, v100
	v_max3_f32 v100, v100, v84, v85
	v_max3_f32 v100, v100, v86, v87
	v_max3_f32 v100, v100, v88, v89
	v_max3_f32 v100, v100, v90, v91
	v_max3_f32 v100, v100, v92, v93
	v_max3_f32 v100, v100, v94, v95
	v_mfma_f32_32x32x16_bf16 v[18:33], v[104:107], v[120:123], v[18:33]
	v_max3_f32 v100, v100, v96, v97
	v_max3_f32 v100, v100, v66, v67
	v_max3_f32 v100, v100, v68, v69
	v_max3_f32 v100, v100, v70, v71
	v_max3_f32 v100, v100, v72, v73
	v_max3_f32 v100, v100, v74, v75
	v_max3_f32 v100, v100, v76, v77
	v_max3_f32 v100, v100, v78, v79
	v_mfma_f32_32x32x16_bf16 v[18:33], v[108:111], v[124:127], v[18:33]
	v_max3_f32 v100, v100, v80, v81
	v_mov_b32_e32 v101, v100
	s_nop 1
	v_permlane32_swap_b32_e32 v100, v101
	v_max_f32_e32 v101, v101, v101
	v_max_f32_e32 v100, v100, v100
	v_max_f32_e32 v100, v100, v101
	v_sub_f32_e32 v101, v100, v142
	s_mov_b32 s2, 0x42800000
	v_cmp_ge_f32_e32 vcc, s2, v101
	v_max_f32_e32 v101, v142, v142
	v_max_f32_e32 v101, v101, v100
	v_mfma_f32_32x32x16_bf16 v[18:33], v[112:115], v[128:131], v[18:33]
	v_sub_f32_e32 v100, v142, v101
	v_mul_f32_e32 v100, 0x3e38aa3b, v100
	v_exp_f32_e32 v100, v100
	s_cmp_eq_u64 vcc, exec
	s_cselect_b64 s[2:3], -1, 0
	v_cndmask_b32_e64 v100, v100, 1.0, s[2:3]
	v_cmp_gt_f32_e32 vcc, 1.0, v100
	s_barrier
	s_cbranch_vccz .LBB0_717
	s_and_saveexec_b64 s[4:5], s[0:1]
	ds_write_b32 v208, v100 offset:128
	s_or_b64 exec, exec, s[4:5]
	s_waitcnt lgkmcnt(0)
	v_add_u32_e32 v114, v207, v0
	ds_read_b128 v[102:105], v114 offset:224
	ds_read_b128 v[106:109], v114 offset:192
	ds_read_b128 v[110:113], v114 offset:160
	ds_read_b128 v[114:117], v114 offset:128
	s_waitcnt lgkmcnt(3)
	v_pk_mul_f32 v[14:15], v[14:15], v[102:103]
	s_waitcnt lgkmcnt(2)
	v_pk_mul_f32 v[10:11], v[10:11], v[106:107]
	s_waitcnt lgkmcnt(1)
	v_pk_mul_f32 v[6:7], v[6:7], v[110:111]
	v_pk_mul_f32 v[16:17], v[16:17], v[104:105]
	v_pk_mul_f32 v[12:13], v[12:13], v[108:109]
	v_pk_mul_f32 v[8:9], v[8:9], v[112:113]
	s_waitcnt lgkmcnt(0)
	v_pk_mul_f32 v[4:5], v[4:5], v[116:117]
	v_pk_mul_f32 v[2:3], v[2:3], v[114:115]
	v_pk_mul_f32 v[62:63], v[102:103], v[62:63]
	v_pk_mul_f32 v[58:59], v[106:107], v[58:59]
	v_pk_mul_f32 v[54:55], v[110:111], v[54:55]
	v_pk_mul_f32 v[64:65], v[104:105], v[64:65]
	v_pk_mul_f32 v[60:61], v[108:109], v[60:61]
	v_pk_mul_f32 v[56:57], v[112:113], v[56:57]
	v_pk_mul_f32 v[52:53], v[116:117], v[52:53]
	v_pk_mul_f32 v[50:51], v[114:115], v[50:51]
	v_pk_mul_f32 v[46:47], v[102:103], v[46:47]
	v_pk_mul_f32 v[42:43], v[106:107], v[42:43]
	v_pk_mul_f32 v[38:39], v[110:111], v[38:39]
	v_pk_mul_f32 v[48:49], v[104:105], v[48:49]
	v_pk_mul_f32 v[44:45], v[108:109], v[44:45]
	v_pk_mul_f32 v[40:41], v[112:113], v[40:41]
	v_pk_mul_f32 v[36:37], v[116:117], v[36:37]
	v_pk_mul_f32 v[34:35], v[114:115], v[34:35]
	v_pk_mul_f32 v[30:31], v[102:103], v[30:31]
	v_pk_mul_f32 v[26:27], v[106:107], v[26:27]
	v_pk_mul_f32 v[22:23], v[110:111], v[22:23]
	v_pk_mul_f32 v[32:33], v[104:105], v[32:33]
	v_pk_mul_f32 v[28:29], v[108:109], v[28:29]
	v_pk_mul_f32 v[24:25], v[112:113], v[24:25]
	v_pk_mul_f32 v[20:21], v[116:117], v[20:21]
	v_pk_mul_f32 v[18:19], v[114:115], v[18:19]
